# cmp_finish inner loop: two batches of w2 loads in flight (double-buffered registers), on top of EpiConv dwordx4 stores + dead zero-init removal
# speedup vs baseline: 1.0193x; 1.0024x over previous
.LBB0_414:
	global_load_dwordx4 v[130:133], v[64:65], off
	global_load_dwordx4 v[134:137], v[66:67], off
	global_load_dwordx4 v[138:141], v[68:69], off
	global_load_dwordx4 v[142:145], v[70:71], off
	global_load_dwordx4 v[146:149], v[72:73], off
	global_load_dwordx4 v[150:153], v[74:75], off
	global_load_dwordx4 v[154:157], v[76:77], off
	global_load_dwordx4 v[158:161], v[78:79], off
	global_load_dwordx4 v[0:3], v[80:81], off
	global_load_dwordx4 v[4:7], v[82:83], off
	global_load_dwordx4 v[8:11], v[84:85], off
	global_load_dwordx4 v[12:15], v[86:87], off
	global_load_dwordx4 v[16:19], v[88:89], off
	global_load_dwordx4 v[20:23], v[90:91], off
	global_load_dwordx4 v[24:27], v[92:93], off
	global_load_dwordx4 v[28:31], v[94:95], off
	global_load_dwordx4 v[32:35], v[96:97], off
	global_load_dwordx4 v[36:39], v[98:99], off
	global_load_dwordx4 v[40:43], v[100:101], off
	global_load_dwordx4 v[44:47], v[102:103], off
	global_load_dwordx4 v[48:51], v[104:105], off
	global_load_dwordx4 v[162:165], v[106:107], off
	global_load_dwordx4 v[166:169], v[108:109], off
	global_load_dwordx4 v[170:173], v[110:111], off
	global_load_dwordx4 v[174:177], v[112:113], off
	global_load_dwordx4 v[178:181], v[114:115], off
	global_load_dwordx4 v[182:185], v[116:117], off
	global_load_dwordx4 v[186:189], v[118:119], off
	global_load_dwordx4 v[190:193], v[120:121], off
	global_load_dwordx4 v[194:197], v[122:123], off
	global_load_dwordx4 v[198:201], v[124:125], off
	global_load_dwordx4 v[202:205], v[126:127], off
	s_ashr_i32 s3, s2, 31
	s_lshl_b64 s[4:5], s[2:3], 10
	v_lshl_add_u64 v[234:235], v[54:55], 0, s[4:5]
	v_add_co_u32_e32 v210, vcc, s6, v234
	s_mov_b64 s[4:5], 0
	s_nop 0
	v_addc_co_u32_e32 v211, vcc, 0, v235, vcc
	v_add_co_u32_e32 v214, vcc, s7, v234
	s_mov_b32 s0, s8
	s_nop 0
	v_addc_co_u32_e32 v215, vcc, 0, v235, vcc
	v_add_co_u32_e32 v218, vcc, s9, v234
	s_waitcnt vmcnt(31)
	v_pk_add_f32 v[130:131], v[130:131], 0 op_sel_hi:[1,0]
	v_addc_co_u32_e32 v219, vcc, 0, v235, vcc
	v_add_co_u32_e32 v222, vcc, s10, v234
	s_waitcnt vmcnt(30)
	v_pk_add_f32 v[134:135], v[134:135], 0 op_sel_hi:[1,0]
	v_addc_co_u32_e32 v223, vcc, 0, v235, vcc
	v_add_co_u32_e32 v226, vcc, s11, v234
	s_waitcnt vmcnt(28)
	v_pk_add_f32 v[134:135], v[134:135], v[142:143]
	v_addc_co_u32_e32 v227, vcc, 0, v235, vcc
	v_add_co_u32_e32 v230, vcc, s12, v234
	s_waitcnt vmcnt(26)
	v_pk_add_f32 v[134:135], v[134:135], v[150:151]
	v_addc_co_u32_e32 v231, vcc, 0, v235, vcc
	s_waitcnt vmcnt(24)
	v_pk_add_f32 v[242:243], v[134:135], v[158:159]
	v_add_co_u32_e32 v134, vcc, s13, v234
	v_pk_add_f32 v[130:131], v[130:131], v[138:139]
	s_nop 0
	v_addc_co_u32_e32 v135, vcc, 0, v235, vcc
	v_add_co_u32_e32 v138, vcc, s14, v234
	v_pk_add_f32 v[130:131], v[130:131], v[146:147]
	s_nop 0
	v_addc_co_u32_e32 v139, vcc, 0, v235, vcc
	v_add_co_u32_e32 v142, vcc, s15, v234
	v_pk_add_f32 v[132:133], v[132:133], 0 op_sel_hi:[1,0]
	s_nop 0
	v_addc_co_u32_e32 v143, vcc, 0, v235, vcc
	v_add_co_u32_e32 v146, vcc, s16, v234
	v_pk_add_f32 v[238:239], v[130:131], v[154:155]
	s_nop 0
	v_addc_co_u32_e32 v147, vcc, 0, v235, vcc
	v_add_co_u32_e32 v150, vcc, s17, v234
	v_pk_add_f32 v[136:137], v[136:137], 0 op_sel_hi:[1,0]
	s_nop 0
	v_addc_co_u32_e32 v151, vcc, 0, v235, vcc
	v_add_co_u32_e32 v154, vcc, s18, v234
	v_pk_add_f32 v[132:133], v[132:133], v[140:141]
	s_nop 0
	v_addc_co_u32_e32 v155, vcc, 0, v235, vcc
	v_pk_add_f32 v[136:137], v[136:137], v[144:145]
	v_pk_add_f32 v[132:133], v[132:133], v[148:149]
	v_add_co_u32_e32 v158, vcc, s19, v234
	global_load_dwordx4 v[206:209], v[234:235], off
	s_nop 0
	global_load_dwordx4 v[210:213], v[210:211], off
	s_nop 0
	global_load_dwordx4 v[214:217], v[214:215], off
	s_nop 0
	global_load_dwordx4 v[218:221], v[218:219], off
	s_nop 0
	global_load_dwordx4 v[222:225], v[222:223], off
	s_nop 0
	global_load_dwordx4 v[226:229], v[226:227], off
	v_pk_add_f32 v[136:137], v[136:137], v[152:153]
	v_pk_add_f32 v[132:133], v[132:133], v[156:157]
	v_addc_co_u32_e32 v159, vcc, 0, v235, vcc
	v_pk_add_f32 v[240:241], v[136:137], v[160:161]
	s_waitcnt vmcnt(29)
	v_pk_add_f32 v[2:3], v[132:133], v[2:3]
	global_load_dwordx4 v[130:133], v[230:231], off
	s_nop 0
	global_load_dwordx4 v[134:137], v[134:135], off
	v_add_co_u32_e32 v230, vcc, s20, v234
	global_load_dwordx4 v[138:141], v[138:139], off
	s_nop 0
	global_load_dwordx4 v[142:145], v[142:143], off
	v_addc_co_u32_e32 v231, vcc, 0, v235, vcc
	global_load_dwordx4 v[146:149], v[146:147], off
	s_nop 0
	global_load_dwordx4 v[150:153], v[150:151], off
	v_add_co_u32_e32 v234, vcc, s21, v234
	global_load_dwordx4 v[154:157], v[154:155], off
	s_nop 0
	global_load_dwordx4 v[158:161], v[158:159], off
	v_addc_co_u32_e32 v235, vcc, 0, v235, vcc
	global_load_dwordx4 v[230:233], v[230:231], off
	v_pk_add_f32 v[0:1], v[238:239], v[0:1]
	global_load_dwordx4 v[234:237], v[234:235], off
	s_waitcnt vmcnt(38)
	v_pk_add_f32 v[6:7], v[240:241], v[6:7]
	v_pk_add_f32 v[4:5], v[242:243], v[4:5]
	s_waitcnt vmcnt(37)
	v_pk_add_f32 v[2:3], v[2:3], v[10:11]
	v_pk_add_f32 v[0:1], v[0:1], v[8:9]
	s_waitcnt vmcnt(36)
	v_pk_add_f32 v[6:7], v[6:7], v[14:15]
	v_pk_add_f32 v[4:5], v[4:5], v[12:13]
	s_waitcnt vmcnt(35)
	v_pk_add_f32 v[2:3], v[2:3], v[18:19]
	v_pk_add_f32 v[0:1], v[0:1], v[16:17]
	s_waitcnt vmcnt(34)
	v_pk_add_f32 v[6:7], v[6:7], v[22:23]
	v_pk_add_f32 v[4:5], v[4:5], v[20:21]
	s_waitcnt vmcnt(33)
	v_pk_add_f32 v[2:3], v[2:3], v[26:27]
	v_pk_add_f32 v[0:1], v[0:1], v[24:25]
	s_waitcnt vmcnt(32)
	v_pk_add_f32 v[6:7], v[6:7], v[30:31]
	v_pk_add_f32 v[4:5], v[4:5], v[28:29]
	s_waitcnt vmcnt(31)
	v_pk_add_f32 v[2:3], v[2:3], v[34:35]
	v_pk_add_f32 v[0:1], v[0:1], v[32:33]
	s_waitcnt vmcnt(30)
	v_pk_add_f32 v[6:7], v[6:7], v[38:39]
	v_pk_add_f32 v[4:5], v[4:5], v[36:37]
	s_waitcnt vmcnt(29)
	v_pk_add_f32 v[2:3], v[2:3], v[42:43]
	v_pk_add_f32 v[0:1], v[0:1], v[40:41]
	s_waitcnt vmcnt(28)
	v_pk_add_f32 v[6:7], v[6:7], v[46:47]
	v_pk_add_f32 v[4:5], v[4:5], v[44:45]
	s_waitcnt vmcnt(27)
	v_pk_add_f32 v[2:3], v[2:3], v[50:51]
	v_pk_add_f32 v[0:1], v[0:1], v[48:49]
	s_waitcnt vmcnt(26)
	v_pk_add_f32 v[6:7], v[6:7], v[164:165]
	v_pk_add_f32 v[4:5], v[4:5], v[162:163]
	s_waitcnt vmcnt(25)
	v_pk_add_f32 v[2:3], v[2:3], v[168:169]
	v_pk_add_f32 v[0:1], v[0:1], v[166:167]
	s_waitcnt vmcnt(24)
	v_pk_add_f32 v[6:7], v[6:7], v[172:173]
	v_pk_add_f32 v[4:5], v[4:5], v[170:171]
	s_waitcnt vmcnt(23)
	v_pk_add_f32 v[2:3], v[2:3], v[176:177]
	v_pk_add_f32 v[0:1], v[0:1], v[174:175]
	s_waitcnt vmcnt(22)
	v_pk_add_f32 v[6:7], v[6:7], v[180:181]
	v_pk_add_f32 v[4:5], v[4:5], v[178:179]
	s_waitcnt vmcnt(21)
	v_pk_add_f32 v[2:3], v[2:3], v[184:185]
	v_pk_add_f32 v[0:1], v[0:1], v[182:183]
	s_waitcnt vmcnt(20)
	v_pk_add_f32 v[6:7], v[6:7], v[188:189]
	v_pk_add_f32 v[4:5], v[4:5], v[186:187]
	s_waitcnt vmcnt(19)
	v_pk_add_f32 v[2:3], v[2:3], v[192:193]
	v_pk_add_f32 v[0:1], v[0:1], v[190:191]
	s_waitcnt vmcnt(18)
	v_pk_add_f32 v[6:7], v[6:7], v[196:197]
	v_pk_add_f32 v[4:5], v[4:5], v[194:195]
	s_waitcnt vmcnt(17)
	v_pk_add_f32 v[2:3], v[2:3], v[200:201]
	v_pk_add_f32 v[0:1], v[0:1], v[198:199]
	s_waitcnt vmcnt(16)
	v_pk_add_f32 v[6:7], v[6:7], v[204:205]
	v_pk_add_f32 v[4:5], v[4:5], v[202:203]
	s_waitcnt vmcnt(15)
	v_pk_add_f32 v[2:3], v[2:3], v[208:209]
	v_pk_add_f32 v[0:1], v[0:1], v[206:207]
	s_waitcnt vmcnt(14)
	v_pk_add_f32 v[6:7], v[6:7], v[212:213]
	v_pk_add_f32 v[4:5], v[4:5], v[210:211]
	s_waitcnt vmcnt(13)
	v_pk_add_f32 v[2:3], v[2:3], v[216:217]
	v_pk_add_f32 v[0:1], v[0:1], v[214:215]
	s_waitcnt vmcnt(12)
	v_pk_add_f32 v[6:7], v[6:7], v[220:221]
	v_pk_add_f32 v[4:5], v[4:5], v[218:219]
	s_waitcnt vmcnt(11)
	v_pk_add_f32 v[2:3], v[2:3], v[224:225]
	v_pk_add_f32 v[0:1], v[0:1], v[222:223]
	s_waitcnt vmcnt(10)
	v_pk_add_f32 v[6:7], v[6:7], v[228:229]
	v_pk_add_f32 v[4:5], v[4:5], v[226:227]
	s_waitcnt vmcnt(9)
	v_pk_add_f32 v[2:3], v[2:3], v[132:133]
	v_pk_add_f32 v[0:1], v[0:1], v[130:131]
	s_waitcnt vmcnt(8)
	v_pk_add_f32 v[6:7], v[6:7], v[136:137]
	v_pk_add_f32 v[4:5], v[4:5], v[134:135]
	s_waitcnt vmcnt(7)
	v_pk_add_f32 v[2:3], v[2:3], v[140:141]
	v_pk_add_f32 v[0:1], v[0:1], v[138:139]
	s_waitcnt vmcnt(6)
	v_pk_add_f32 v[6:7], v[6:7], v[144:145]
	v_pk_add_f32 v[4:5], v[4:5], v[142:143]
	s_waitcnt vmcnt(5)
	v_pk_add_f32 v[2:3], v[2:3], v[148:149]
	v_pk_add_f32 v[0:1], v[0:1], v[146:147]
	s_waitcnt vmcnt(4)
	v_pk_add_f32 v[6:7], v[6:7], v[152:153]
	v_pk_add_f32 v[4:5], v[4:5], v[150:151]
	s_waitcnt vmcnt(3)
	v_pk_add_f32 v[2:3], v[2:3], v[156:157]
	v_pk_add_f32 v[0:1], v[0:1], v[154:155]
	s_waitcnt vmcnt(2)
	v_pk_add_f32 v[6:7], v[6:7], v[160:161]
	v_pk_add_f32 v[4:5], v[4:5], v[158:159]
	s_waitcnt vmcnt(1)
	v_pk_add_f32 v[0:1], v[0:1], v[230:231]
	v_pk_add_f32 v[2:3], v[2:3], v[232:233]
	v_mul_f32_e32 v8, 0xbfb8aa3b, v0
	s_waitcnt vmcnt(0)
	v_pk_add_f32 v[6:7], v[6:7], v[236:237]
	v_pk_add_f32 v[4:5], v[4:5], v[234:235]
	v_mul_f32_e32 v9, 0xbfb8aa3b, v1
	v_mul_f32_e32 v10, 0xbfb8aa3b, v2
	v_mul_f32_e32 v11, 0xbfb8aa3b, v3
	v_exp_f32_e32 v8, v8
	v_exp_f32_e32 v9, v9
	v_exp_f32_e32 v10, v10
	v_exp_f32_e32 v11, v11
	v_mul_f32_e32 v12, 0xbfb8aa3b, v4
	v_mul_f32_e32 v13, 0xbfb8aa3b, v5
	v_mul_f32_e32 v14, 0xbfb8aa3b, v6
	v_mul_f32_e32 v15, 0xbfb8aa3b, v7
	v_exp_f32_e32 v12, v12
	v_exp_f32_e32 v13, v13
	v_exp_f32_e32 v14, v14
	v_exp_f32_e32 v15, v15
	v_add_f32_e32 v8, 1.0, v8
	v_add_f32_e32 v9, 1.0, v9
	v_add_f32_e32 v10, 1.0, v10
	v_add_f32_e32 v11, 1.0, v11
	v_rcp_f32_e32 v8, v8
	v_rcp_f32_e32 v9, v9
	v_rcp_f32_e32 v10, v10
	v_rcp_f32_e32 v11, v11
	v_add_f32_e32 v12, 1.0, v12
	v_add_f32_e32 v13, 1.0, v13
	v_add_f32_e32 v14, 1.0, v14
	v_add_f32_e32 v15, 1.0, v15
	v_rcp_f32_e32 v12, v12
	v_rcp_f32_e32 v14, v14
	v_rcp_f32_e32 v15, v15
	v_rcp_f32_e32 v13, v13
	v_pk_mul_f32 v[2:3], v[2:3], v[10:11]
	v_pk_mul_f32 v[0:1], v[0:1], v[8:9]
	v_pk_mul_f32 v[6:7], v[6:7], v[14:15]
	v_pk_mul_f32 v[4:5], v[4:5], v[12:13]
	ds_write_b128 v128, v[0:3]
	ds_write_b128 v128, v[4:7] offset:1024
	s_waitcnt lgkmcnt(0)
	v_mov_b32_e32 v2, 0
	v_mov_b32_e32 v3, v53
	v_mov_b32_e32 v0, 0
	v_mov_b32_e32 v1, v53
	v_mov_b32_e32 v6, 0
	v_mov_b32_e32 v7, v53
	v_mov_b32_e32 v4, 0
	v_mov_b32_e32 v5, v53
	v_lshl_add_u64 v[186:187], v[56:57], 0, s[4:5]
	v_lshl_add_u64 v[188:189], v[58:59], 0, s[4:5]
	global_load_dword v40, v[186:187], off
	global_load_dword v41, v[186:187], off offset:256
	global_load_dword v42, v[186:187], off offset:512
	global_load_dword v43, v[186:187], off offset:768
	global_load_dword v44, v[186:187], off offset:1024
	global_load_dword v45, v[186:187], off offset:1280
	global_load_dword v46, v[186:187], off offset:1536
	global_load_dword v47, v[186:187], off offset:1792
	global_load_dword v48, v[188:189], off
	global_load_dword v49, v[188:189], off offset:256
	global_load_dword v50, v[188:189], off offset:512
	global_load_dword v51, v[188:189], off offset:768
	global_load_dword v130, v[188:189], off offset:1024
	global_load_dword v131, v[188:189], off offset:1280
	global_load_dword v132, v[188:189], off offset:1536
	global_load_dword v133, v[188:189], off offset:1792
	global_load_dword v134, v[186:187], off offset:2048
	global_load_dword v135, v[186:187], off offset:2304
	global_load_dword v136, v[186:187], off offset:2560
	global_load_dword v137, v[186:187], off offset:2816
	global_load_dword v138, v[186:187], off offset:3072
	global_load_dword v139, v[186:187], off offset:3328
	global_load_dword v140, v[186:187], off offset:3584
	global_load_dword v141, v[186:187], off offset:3840
	global_load_dword v142, v[188:189], off offset:2048
	global_load_dword v143, v[188:189], off offset:2304
	global_load_dword v144, v[188:189], off offset:2560
	global_load_dword v145, v[188:189], off offset:2816
	global_load_dword v146, v[188:189], off offset:3072
	global_load_dword v148, v[188:189], off offset:3584
	global_load_dword v149, v[188:189], off offset:3840
	global_load_dword v147, v[188:189], off offset:3328
.Lcf_loop:
	s_add_u32 s4, s4, 0x1000
	s_addc_u32 s5, s5, 0
	v_lshl_add_u64 v[182:183], v[56:57], 0, s[4:5]
	v_lshl_add_u64 v[184:185], v[58:59], 0, s[4:5]
	global_load_dword v150, v[182:183], off
	global_load_dword v151, v[182:183], off offset:256
	global_load_dword v152, v[182:183], off offset:512
	global_load_dword v153, v[182:183], off offset:768
	global_load_dword v154, v[182:183], off offset:1024
	global_load_dword v155, v[182:183], off offset:1280
	global_load_dword v156, v[182:183], off offset:1536
	global_load_dword v157, v[182:183], off offset:1792
	global_load_dword v158, v[184:185], off
	global_load_dword v159, v[184:185], off offset:256
	global_load_dword v160, v[184:185], off offset:512
	global_load_dword v161, v[184:185], off offset:768
	global_load_dword v162, v[184:185], off offset:1024
	global_load_dword v163, v[184:185], off offset:1280
	global_load_dword v164, v[184:185], off offset:1536
	global_load_dword v165, v[184:185], off offset:1792
	global_load_dword v166, v[182:183], off offset:2048
	global_load_dword v167, v[182:183], off offset:2304
	global_load_dword v168, v[182:183], off offset:2560
	global_load_dword v169, v[182:183], off offset:2816
	global_load_dword v170, v[182:183], off offset:3072
	global_load_dword v171, v[182:183], off offset:3328
	global_load_dword v172, v[182:183], off offset:3584
	global_load_dword v173, v[182:183], off offset:3840
	global_load_dword v174, v[184:185], off offset:2048
	global_load_dword v175, v[184:185], off offset:2304
	global_load_dword v176, v[184:185], off offset:2560
	global_load_dword v177, v[184:185], off offset:2816
	global_load_dword v178, v[184:185], off offset:3072
	global_load_dword v180, v[184:185], off offset:3584
	global_load_dword v181, v[184:185], off offset:3840
	v_mov_b32_e32 v36, s0
	ds_read_b128 v[8:11], v36
	ds_read_b128 v[12:15], v36 offset:16
	ds_read_b128 v[16:19], v36 offset:32
	ds_read_b128 v[20:23], v36 offset:48
	ds_read_b128 v[24:27], v36 offset:1024
	ds_read_b128 v[28:31], v36 offset:1040
	ds_read_b128 v[32:35], v36 offset:1056
	ds_read_b128 v[36:39], v36 offset:1072
	s_add_i32 s0, s0, 64
	s_waitcnt vmcnt(61) lgkmcnt(7)
	v_pk_fma_f32 v[6:7], v[8:9], v[40:41], v[6:7]
	global_load_dword v179, v[184:185], off offset:3328
	s_waitcnt vmcnt(60)
	v_pk_fma_f32 v[4:5], v[10:11], v[42:43], v[4:5]
	s_waitcnt vmcnt(58) lgkmcnt(6)
	v_pk_fma_f32 v[6:7], v[12:13], v[44:45], v[6:7]
	s_waitcnt vmcnt(56)
	v_pk_fma_f32 v[4:5], v[14:15], v[46:47], v[4:5]
	s_waitcnt vmcnt(54) lgkmcnt(3)
	v_pk_fma_f32 v[2:3], v[24:25], v[48:49], v[2:3]
	s_waitcnt vmcnt(52)
	v_pk_fma_f32 v[0:1], v[26:27], v[50:51], v[0:1]
	s_waitcnt vmcnt(50) lgkmcnt(2)
	v_pk_fma_f32 v[2:3], v[28:29], v[130:131], v[2:3]
	s_waitcnt vmcnt(48)
	v_pk_fma_f32 v[0:1], v[30:31], v[132:133], v[0:1]
	s_waitcnt vmcnt(46)
	v_pk_fma_f32 v[6:7], v[16:17], v[134:135], v[6:7]
	s_waitcnt vmcnt(44)
	v_pk_fma_f32 v[4:5], v[18:19], v[136:137], v[4:5]
	s_waitcnt vmcnt(42)
	v_pk_fma_f32 v[6:7], v[20:21], v[138:139], v[6:7]
	s_waitcnt vmcnt(40)
	v_pk_fma_f32 v[4:5], v[22:23], v[140:141], v[4:5]
	s_waitcnt vmcnt(38) lgkmcnt(1)
	v_pk_fma_f32 v[2:3], v[32:33], v[142:143], v[2:3]
	s_waitcnt vmcnt(36)
	v_pk_fma_f32 v[0:1], v[34:35], v[144:145], v[0:1]
	s_waitcnt vmcnt(33) lgkmcnt(0)
	v_pk_fma_f32 v[0:1], v[38:39], v[148:149], v[0:1]
	s_waitcnt vmcnt(32)
	v_pk_fma_f32 v[2:3], v[36:37], v[146:147], v[2:3]
	s_add_u32 s4, s4, 0x1000
	s_addc_u32 s5, s5, 0
	s_cmp_eq_u32 s4, 0x10000
	s_cselect_b32 s26, 0, s4
	s_cselect_b32 s27, 0, s5
	v_lshl_add_u64 v[186:187], v[56:57], 0, s[26:27]
	v_lshl_add_u64 v[188:189], v[58:59], 0, s[26:27]
	global_load_dword v40, v[186:187], off
	global_load_dword v41, v[186:187], off offset:256
	global_load_dword v42, v[186:187], off offset:512
	global_load_dword v43, v[186:187], off offset:768
	global_load_dword v44, v[186:187], off offset:1024
	global_load_dword v45, v[186:187], off offset:1280
	global_load_dword v46, v[186:187], off offset:1536
	global_load_dword v47, v[186:187], off offset:1792
	global_load_dword v48, v[188:189], off
	global_load_dword v49, v[188:189], off offset:256
	global_load_dword v50, v[188:189], off offset:512
	global_load_dword v51, v[188:189], off offset:768
	global_load_dword v130, v[188:189], off offset:1024
	global_load_dword v131, v[188:189], off offset:1280
	global_load_dword v132, v[188:189], off offset:1536
	global_load_dword v133, v[188:189], off offset:1792
	global_load_dword v134, v[186:187], off offset:2048
	global_load_dword v135, v[186:187], off offset:2304
	global_load_dword v136, v[186:187], off offset:2560
	global_load_dword v137, v[186:187], off offset:2816
	global_load_dword v138, v[186:187], off offset:3072
	global_load_dword v139, v[186:187], off offset:3328
	global_load_dword v140, v[186:187], off offset:3584
	global_load_dword v141, v[186:187], off offset:3840
	global_load_dword v142, v[188:189], off offset:2048
	global_load_dword v143, v[188:189], off offset:2304
	global_load_dword v144, v[188:189], off offset:2560
	global_load_dword v145, v[188:189], off offset:2816
	global_load_dword v146, v[188:189], off offset:3072
	global_load_dword v148, v[188:189], off offset:3584
	global_load_dword v149, v[188:189], off offset:3840
	v_mov_b32_e32 v36, s0
	ds_read_b128 v[8:11], v36
	ds_read_b128 v[12:15], v36 offset:16
	ds_read_b128 v[16:19], v36 offset:32
	ds_read_b128 v[20:23], v36 offset:48
	ds_read_b128 v[24:27], v36 offset:1024
	ds_read_b128 v[28:31], v36 offset:1040
	ds_read_b128 v[32:35], v36 offset:1056
	ds_read_b128 v[36:39], v36 offset:1072
	s_add_i32 s0, s0, 64
	s_waitcnt vmcnt(61) lgkmcnt(7)
	v_pk_fma_f32 v[6:7], v[8:9], v[150:151], v[6:7]
	global_load_dword v147, v[188:189], off offset:3328
	s_waitcnt vmcnt(60)
	v_pk_fma_f32 v[4:5], v[10:11], v[152:153], v[4:5]
	s_waitcnt vmcnt(58) lgkmcnt(6)
	v_pk_fma_f32 v[6:7], v[12:13], v[154:155], v[6:7]
	s_waitcnt vmcnt(56)
	v_pk_fma_f32 v[4:5], v[14:15], v[156:157], v[4:5]
	s_waitcnt vmcnt(54) lgkmcnt(3)
	v_pk_fma_f32 v[2:3], v[24:25], v[158:159], v[2:3]
	s_waitcnt vmcnt(52)
	v_pk_fma_f32 v[0:1], v[26:27], v[160:161], v[0:1]
	s_waitcnt vmcnt(50) lgkmcnt(2)
	v_pk_fma_f32 v[2:3], v[28:29], v[162:163], v[2:3]
	s_waitcnt vmcnt(48)
	v_pk_fma_f32 v[0:1], v[30:31], v[164:165], v[0:1]
	s_waitcnt vmcnt(46)
	v_pk_fma_f32 v[6:7], v[16:17], v[166:167], v[6:7]
	s_waitcnt vmcnt(44)
	v_pk_fma_f32 v[4:5], v[18:19], v[168:169], v[4:5]
	s_waitcnt vmcnt(42)
	v_pk_fma_f32 v[6:7], v[20:21], v[170:171], v[6:7]
	s_waitcnt vmcnt(40)
	v_pk_fma_f32 v[4:5], v[22:23], v[172:173], v[4:5]
	s_waitcnt vmcnt(38) lgkmcnt(1)
	v_pk_fma_f32 v[2:3], v[32:33], v[174:175], v[2:3]
	s_waitcnt vmcnt(36)
	v_pk_fma_f32 v[0:1], v[34:35], v[176:177], v[0:1]
	s_waitcnt vmcnt(33) lgkmcnt(0)
	v_pk_fma_f32 v[0:1], v[38:39], v[180:181], v[0:1]
	s_waitcnt vmcnt(32)
	v_pk_fma_f32 v[2:3], v[36:37], v[178:179], v[2:3]
	s_cmp_eq_u32 s4, 0x10000
	s_cbranch_scc0 .Lcf_loop
	s_waitcnt vmcnt(0)
	s_branch .Lcf_after
	s_nop 0
	s_nop 0
	s_nop 0
	s_nop 0
	s_nop 0
	s_nop 0
	s_nop 0
	s_nop 0
	s_nop 0
	s_nop 0
	s_nop 0
	s_nop 0
	s_nop 0
	s_nop 0
	s_nop 0
	s_nop 0
	s_nop 0
	s_nop 0
	s_nop 0
	s_nop 0
	s_nop 0
	s_nop 0
	s_nop 0
	s_nop 0
	s_nop 0
	s_nop 0
	s_nop 0
	s_nop 0
	s_nop 0
	s_nop 0
	s_nop 0
	s_nop 0
	s_nop 0
	s_nop 0
	s_nop 0
	s_nop 0
	s_nop 0
	s_nop 0
	s_nop 0
	s_nop 0
	s_nop 0
	s_nop 0
	s_nop 0
	s_nop 0
	s_nop 0
.Lcf_after:
	s_and_b32 s0, s2, 0x7f
	v_add_f32_e32 v6, v6, v7
	v_add_f32_e32 v4, v4, v5
	s_cmpk_eq_i32 s0, 0x7f
	v_add_f32_e32 v4, v6, v4
	v_add_f32_e32 v2, v2, v3
	v_add_f32_e32 v0, v0, v1
	s_cselect_b64 s[4:5], -1, 0
	v_add_f32_e32 v2, v2, v0
	v_cndmask_b32_e64 v0, v4, 0, s[4:5]
	v_bfe_u32 v1, v0, 16, 1
	s_lshl_b64 s[26:27], s[2:3], 7
	v_add3_u32 v3, v0, v1, s24
	v_lshl_add_u64 v[0:1], v[60:61], 0, s[26:27]
	global_store_short_d16_hi v[0:1], v3, off
	v_cndmask_b32_e64 v0, v2, 0, s[4:5]
	s_ashr_i32 s4, s2, 7
	s_ashr_i32 s5, s4, 31
	v_bfe_u32 v1, v0, 16, 1
	s_lshl_b64 s[4:5], s[4:5], 14
	v_add3_u32 v2, v0, v1, s24
	v_lshl_add_u64 v[0:1], v[62:63], 0, s[4:5]
	s_lshl_b32 s0, s0, 1
	v_lshl_add_u64 v[0:1], v[0:1], 0, s[0:1]
	v_add_co_u32_e32 v0, vcc, 0x40000, v0
	s_add_i32 s2, s2, s71
	s_nop 0
	v_addc_co_u32_e32 v1, vcc, 0, v1, vcc
	global_store_short_d16_hi v[0:1], v2, off
	s_waitcnt lgkmcnt(0)
	s_cmpk_gt_i32 s2, 0x7ff
	s_cbranch_scc0 .LBB0_414

.LBB0_715:
	s_or_b64 exec, exec, s[56:57]
	s_waitcnt lgkmcnt(0)
	v_mov_b32_dpp v242, v198 row_ror:2 row_mask:0xf bank_mask:0xf
	v_mov_b32_dpp v193, v198 row_ror:1 row_mask:0xf bank_mask:0xf
	v_mov_b32_dpp v242, v188 row_shr:2 row_mask:0xf bank_mask:0xf
	v_mov_b32_dpp v193, v188 row_shr:1 row_mask:0xf bank_mask:0xf
	s_waitcnt vmcnt(0)
	v_fma_f32 v242, v164, v242, v156
	v_fmac_f32_e32 v242, v168, v193
	v_fmac_f32_e32 v242, v188, v172
	v_mul_f32_e32 v193, 0xbfb8aa3b, v242
	v_exp_f32_e32 v193, v193
	v_mov_b32_dpp v243, v194 row_ror:2 row_mask:0xf bank_mask:0xf
	v_mov_b32_dpp v198, v194 row_ror:1 row_mask:0xf bank_mask:0xf
	v_lshl_add_u32 v210, s54, 8, v213
	v_add_f32_e32 v193, 1.0, v193
	v_rcp_f32_e32 v193, v193
	v_mov_b32_dpp v243, v184 row_shr:2 row_mask:0xf bank_mask:0xf
	v_mov_b32_dpp v198, v184 row_shr:1 row_mask:0xf bank_mask:0xf
	v_fma_f32 v194, v144, v243, v160
	v_fmac_f32_e32 v194, v148, v198
	v_fmac_f32_e32 v194, v184, v152
	v_mul_f32_e32 v193, v242, v193
	v_mul_f32_e32 v193, v194, v193
	v_mov_b32_dpp v198, v199 row_ror:2 row_mask:0xf bank_mask:0xf
	v_mov_b32_dpp v194, v199 row_ror:1 row_mask:0xf bank_mask:0xf
	v_mov_b32_dpp v198, v189 row_shr:2 row_mask:0xf bank_mask:0xf
	v_fma_f32 v198, v165, v198, v157
	v_mov_b32_dpp v194, v189 row_shr:1 row_mask:0xf bank_mask:0xf
	v_fmac_f32_e32 v198, v169, v194
	v_fmac_f32_e32 v198, v189, v173
	v_mul_f32_e32 v194, 0xbfb8aa3b, v198
	v_exp_f32_e32 v194, v194
	v_mov_b32_dpp v242, v195 row_ror:2 row_mask:0xf bank_mask:0xf
	v_add_f32_e32 v194, 1.0, v194
	v_rcp_f32_e32 v194, v194
	v_mov_b32_dpp v199, v195 row_ror:1 row_mask:0xf bank_mask:0xf
	v_mov_b32_dpp v242, v185 row_shr:2 row_mask:0xf bank_mask:0xf
	v_fma_f32 v195, v145, v242, v161
	v_mov_b32_dpp v199, v185 row_shr:1 row_mask:0xf bank_mask:0xf
	v_fmac_f32_e32 v195, v149, v199
	v_fmac_f32_e32 v195, v185, v153
	v_mul_f32_e32 v194, v198, v194
	v_mul_f32_e32 v242, v195, v194
	v_mov_b32_dpp v195, v200 row_ror:2 row_mask:0xf bank_mask:0xf
	v_mov_b32_dpp v194, v200 row_ror:1 row_mask:0xf bank_mask:0xf
	v_mov_b32_dpp v195, v190 row_shr:2 row_mask:0xf bank_mask:0xf
	v_mov_b32_dpp v194, v190 row_shr:1 row_mask:0xf bank_mask:0xf
	v_fma_f32 v195, v166, v195, v158
	v_fmac_f32_e32 v195, v170, v194
	v_fmac_f32_e32 v195, v190, v174
	v_mul_f32_e32 v194, 0xbfb8aa3b, v195
	v_exp_f32_e32 v194, v194
	v_mov_b32_dpp v199, v196 row_ror:2 row_mask:0xf bank_mask:0xf
	v_mov_b32_dpp v198, v196 row_ror:1 row_mask:0xf bank_mask:0xf
	v_cvt_pk_bf16_f32 v244, v193, v242
	v_add_f32_e32 v194, 1.0, v194
	v_rcp_f32_e32 v194, v194
	v_mov_b32_dpp v199, v186 row_shr:2 row_mask:0xf bank_mask:0xf
	v_mov_b32_dpp v198, v186 row_shr:1 row_mask:0xf bank_mask:0xf
	v_fma_f32 v196, v146, v199, v162
	v_fmac_f32_e32 v196, v150, v198
	v_fmac_f32_e32 v196, v186, v154
	v_mul_f32_e32 v194, v195, v194
	v_mul_f32_e32 v200, v196, v194
	v_mov_b32_dpp v195, v201 row_ror:2 row_mask:0xf bank_mask:0xf
	v_mov_b32_dpp v194, v201 row_ror:1 row_mask:0xf bank_mask:0xf
	v_mov_b32_dpp v195, v191 row_shr:2 row_mask:0xf bank_mask:0xf
	v_fma_f32 v195, v167, v195, v159
	v_mov_b32_dpp v194, v191 row_shr:1 row_mask:0xf bank_mask:0xf
	v_fmac_f32_e32 v195, v171, v194
	v_fmac_f32_e32 v195, v191, v175
	v_mul_f32_e32 v194, 0xbfb8aa3b, v195
	v_exp_f32_e32 v194, v194
	v_mov_b32_dpp v198, v197 row_ror:2 row_mask:0xf bank_mask:0xf
	v_add_f32_e32 v194, 1.0, v194
	v_rcp_f32_e32 v194, v194
	v_mov_b32_dpp v196, v197 row_ror:1 row_mask:0xf bank_mask:0xf
	v_mov_b32_dpp v198, v187 row_shr:2 row_mask:0xf bank_mask:0xf
	v_fma_f32 v197, v147, v198, v163
	v_mov_b32_dpp v196, v187 row_shr:1 row_mask:0xf bank_mask:0xf
	v_fmac_f32_e32 v197, v151, v196
	v_fmac_f32_e32 v197, v187, v155
	v_mul_f32_e32 v194, v195, v194
	v_mul_f32_e32 v201, v197, v194
	v_mov_b64_e32 v[194:195], s[12:13]
	v_mad_i64_i32 v[196:197], s[54:55], v210, s77, v[194:195]
	v_lshlrev_b64 v[198:199], 1, v[226:227]
	v_lshl_add_u64 v[196:197], v[196:197], 0, v[198:199]
	v_cvt_pk_bf16_f32 v245, v200, v201
	v_mov_b32_dpp v200, v188 row_ror:2 row_mask:0xf bank_mask:0xf
	v_mov_b32_dpp v193, v188 row_ror:1 row_mask:0xf bank_mask:0xf
	v_mov_b32_dpp v200, v180 row_shr:2 row_mask:0xf bank_mask:0xf
	v_fma_f32 v200, v164, v200, v156
	v_mov_b32_dpp v193, v180 row_shr:1 row_mask:0xf bank_mask:0xf
	v_fmac_f32_e32 v200, v168, v193
	v_fmac_f32_e32 v200, v180, v172
	v_mul_f32_e32 v193, 0xbfb8aa3b, v200
	v_exp_f32_e32 v193, v193
	v_mov_b32_dpp v201, v184 row_ror:2 row_mask:0xf bank_mask:0xf
	s_nop 0
	v_mov_b32_dpp v188, v184 row_ror:1 row_mask:0xf bank_mask:0xf
	v_add_f32_e32 v184, 1.0, v193
	v_rcp_f32_e32 v184, v184
	v_mov_b32_dpp v201, v176 row_shr:2 row_mask:0xf bank_mask:0xf
	v_mov_b32_dpp v188, v176 row_shr:1 row_mask:0xf bank_mask:0xf
	v_fma_f32 v193, v144, v201, v160
	v_fmac_f32_e32 v193, v148, v188
	v_fmac_f32_e32 v193, v176, v152
	v_mul_f32_e32 v184, v200, v184
	v_mul_f32_e32 v188, v193, v184
	v_mov_b32_dpp v193, v189 row_ror:2 row_mask:0xf bank_mask:0xf
	v_mov_b32_dpp v184, v189 row_ror:1 row_mask:0xf bank_mask:0xf
	v_mov_b32_dpp v193, v181 row_shr:2 row_mask:0xf bank_mask:0xf
	v_mov_b32_dpp v184, v181 row_shr:1 row_mask:0xf bank_mask:0xf
	v_fma_f32 v193, v165, v193, v157
	v_fmac_f32_e32 v193, v169, v184
	v_fmac_f32_e32 v193, v181, v173
	v_mul_f32_e32 v184, 0xbfb8aa3b, v193
	v_exp_f32_e32 v184, v184
	v_mov_b32_dpp v200, v185 row_ror:2 row_mask:0xf bank_mask:0xf
	v_mov_b32_dpp v189, v185 row_ror:1 row_mask:0xf bank_mask:0xf
	v_add_f32_e32 v184, 1.0, v184
	v_rcp_f32_e32 v184, v184
	v_mov_b32_dpp v200, v177 row_shr:2 row_mask:0xf bank_mask:0xf
	v_mov_b32_dpp v189, v177 row_shr:1 row_mask:0xf bank_mask:0xf
	v_fma_f32 v185, v145, v200, v161
	v_fmac_f32_e32 v185, v149, v189
	v_fmac_f32_e32 v185, v177, v153
	v_mul_f32_e32 v184, v193, v184
	v_mul_f32_e32 v189, v185, v184
	v_mov_b32_dpp v185, v190 row_ror:2 row_mask:0xf bank_mask:0xf
	v_mov_b32_dpp v184, v190 row_ror:1 row_mask:0xf bank_mask:0xf
	v_mov_b32_dpp v185, v182 row_shr:2 row_mask:0xf bank_mask:0xf
	v_mov_b32_dpp v184, v182 row_shr:1 row_mask:0xf bank_mask:0xf
	v_fma_f32 v185, v166, v185, v158
	v_fmac_f32_e32 v185, v170, v184
	v_fmac_f32_e32 v185, v182, v174
	v_mul_f32_e32 v184, 0xbfb8aa3b, v185
	v_exp_f32_e32 v184, v184
	v_mov_b32_dpp v193, v186 row_ror:2 row_mask:0xf bank_mask:0xf
	v_mov_b32_dpp v190, v186 row_ror:1 row_mask:0xf bank_mask:0xf
	v_cvt_pk_bf16_f32 v242, v188, v189
	v_add_f32_e32 v184, 1.0, v184
	v_rcp_f32_e32 v184, v184
	v_mov_b32_dpp v193, v178 row_shr:2 row_mask:0xf bank_mask:0xf
	v_mov_b32_dpp v190, v178 row_shr:1 row_mask:0xf bank_mask:0xf
	v_fma_f32 v186, v146, v193, v162
	v_fmac_f32_e32 v186, v150, v190
	v_fmac_f32_e32 v186, v178, v154
	v_mul_f32_e32 v184, v185, v184
	v_mul_f32_e32 v186, v186, v184
	v_mov_b32_dpp v185, v191 row_ror:2 row_mask:0xf bank_mask:0xf
	v_mov_b32_dpp v184, v191 row_ror:1 row_mask:0xf bank_mask:0xf
	v_mov_b32_dpp v185, v183 row_shr:2 row_mask:0xf bank_mask:0xf
	v_fma_f32 v185, v167, v185, v159
	v_mov_b32_dpp v184, v183 row_shr:1 row_mask:0xf bank_mask:0xf
	v_fmac_f32_e32 v185, v171, v184
	v_fmac_f32_e32 v185, v183, v175
	v_mul_f32_e32 v184, 0xbfb8aa3b, v185
	v_exp_f32_e32 v184, v184
	v_mov_b32_dpp v190, v187 row_ror:1 row_mask:0xf bank_mask:0xf
	v_mov_b32_e32 v193, 0
	v_add_f32_e32 v184, 1.0, v184
	v_mov_b32_dpp v191, v187 row_ror:2 row_mask:0xf bank_mask:0xf
	v_rcp_f32_e32 v184, v184
	v_mov_b32_dpp v190, v179 row_shr:1 row_mask:0xf bank_mask:0xf
	v_mov_b32_dpp v191, v179 row_shr:2 row_mask:0xf bank_mask:0xf
	v_fma_f32 v187, v147, v191, v163
	v_fmac_f32_e32 v187, v151, v190
	v_fmac_f32_e32 v187, v179, v155
	v_mul_f32_e32 v184, v185, v184
	v_mul_f32_e32 v187, v187, v184
	v_or_b32_e32 v184, 16, v210
	v_mad_i64_i32 v[184:185], s[54:55], v184, s77, v[194:195]
	v_lshl_add_u64 v[184:185], v[184:185], 0, v[198:199]
	v_cvt_pk_bf16_f32 v243, v186, v187
	v_mov_b32_dpp v187, v180 row_ror:2 row_mask:0xf bank_mask:0xf
	v_mov_b32_dpp v186, v180 row_ror:1 row_mask:0xf bank_mask:0xf
	v_mov_b32_dpp v187, v140 row_shr:2 row_mask:0xf bank_mask:0xf
	v_fma_f32 v187, v164, v187, v156
	v_mov_b32_dpp v186, v140 row_shr:1 row_mask:0xf bank_mask:0xf
	v_fmac_f32_e32 v187, v168, v186
	v_fmac_f32_e32 v187, v140, v172
	v_mul_f32_e32 v186, 0xbfb8aa3b, v187
	v_exp_f32_e32 v186, v186
	v_mov_b32_dpp v188, v176 row_ror:2 row_mask:0xf bank_mask:0xf
	s_nop 0
	v_mov_b32_dpp v180, v176 row_ror:1 row_mask:0xf bank_mask:0xf
	v_add_f32_e32 v176, 1.0, v186
	v_rcp_f32_e32 v176, v176
	v_mov_b32_dpp v188, v132 row_shr:2 row_mask:0xf bank_mask:0xf
	v_mov_b32_dpp v180, v132 row_shr:1 row_mask:0xf bank_mask:0xf
	v_fma_f32 v186, v144, v188, v160
	v_fmac_f32_e32 v186, v148, v180
	v_fmac_f32_e32 v186, v132, v152
	v_mul_f32_e32 v176, v187, v176
	v_mul_f32_e32 v180, v186, v176
	v_mov_b32_dpp v186, v181 row_ror:2 row_mask:0xf bank_mask:0xf
	v_mov_b32_dpp v176, v181 row_ror:1 row_mask:0xf bank_mask:0xf
	v_mov_b32_dpp v186, v141 row_shr:2 row_mask:0xf bank_mask:0xf
	v_mov_b32_dpp v176, v141 row_shr:1 row_mask:0xf bank_mask:0xf
	v_fma_f32 v186, v165, v186, v157
	v_fmac_f32_e32 v186, v169, v176
	v_fmac_f32_e32 v186, v141, v173
	v_mul_f32_e32 v176, 0xbfb8aa3b, v186
	v_exp_f32_e32 v176, v176
	v_mov_b32_dpp v187, v177 row_ror:2 row_mask:0xf bank_mask:0xf
	v_mov_b32_dpp v181, v177 row_ror:1 row_mask:0xf bank_mask:0xf
	v_add_f32_e32 v176, 1.0, v176
	v_rcp_f32_e32 v176, v176
	v_mov_b32_dpp v187, v133 row_shr:2 row_mask:0xf bank_mask:0xf
	v_mov_b32_dpp v181, v133 row_shr:1 row_mask:0xf bank_mask:0xf
	v_fma_f32 v177, v145, v187, v161
	v_fmac_f32_e32 v177, v149, v181
	v_fmac_f32_e32 v177, v133, v153
	v_mul_f32_e32 v176, v186, v176
	v_mul_f32_e32 v181, v177, v176
	v_mov_b32_dpp v177, v182 row_ror:2 row_mask:0xf bank_mask:0xf
	v_mov_b32_dpp v176, v182 row_ror:1 row_mask:0xf bank_mask:0xf
	v_mov_b32_dpp v177, v142 row_shr:2 row_mask:0xf bank_mask:0xf
	v_mov_b32_dpp v176, v142 row_shr:1 row_mask:0xf bank_mask:0xf
	v_fma_f32 v177, v166, v177, v158
	v_fmac_f32_e32 v177, v170, v176
	v_fmac_f32_e32 v177, v142, v174
	v_mul_f32_e32 v176, 0xbfb8aa3b, v177
	v_exp_f32_e32 v176, v176
	v_mov_b32_dpp v186, v178 row_ror:2 row_mask:0xf bank_mask:0xf
	v_mov_b32_dpp v182, v178 row_ror:1 row_mask:0xf bank_mask:0xf
	v_cvt_pk_bf16_f32 v200, v180, v181
	v_add_f32_e32 v176, 1.0, v176
	v_rcp_f32_e32 v176, v176
	v_mov_b32_dpp v186, v134 row_shr:2 row_mask:0xf bank_mask:0xf
	v_mov_b32_dpp v182, v134 row_shr:1 row_mask:0xf bank_mask:0xf
	v_fma_f32 v178, v146, v186, v162
	v_fmac_f32_e32 v178, v150, v182
	v_fmac_f32_e32 v178, v134, v154
	v_mul_f32_e32 v176, v177, v176
	v_mul_f32_e32 v178, v178, v176
	v_mov_b32_dpp v177, v183 row_ror:2 row_mask:0xf bank_mask:0xf
	v_mov_b32_dpp v176, v183 row_ror:1 row_mask:0xf bank_mask:0xf
	v_mov_b32_dpp v177, v143 row_shr:2 row_mask:0xf bank_mask:0xf
	v_fma_f32 v177, v167, v177, v159
	v_mov_b32_dpp v176, v143 row_shr:1 row_mask:0xf bank_mask:0xf
	v_fmac_f32_e32 v177, v171, v176
	v_fmac_f32_e32 v177, v143, v175
	v_mul_f32_e32 v176, 0xbfb8aa3b, v177
	v_exp_f32_e32 v176, v176
	v_mov_b32_dpp v182, v179 row_ror:1 row_mask:0xf bank_mask:0xf
	v_add_f32_e32 v176, 1.0, v176
	v_mov_b32_dpp v183, v179 row_ror:2 row_mask:0xf bank_mask:0xf
	v_rcp_f32_e32 v176, v176
	v_mov_b32_dpp v182, v135 row_shr:1 row_mask:0xf bank_mask:0xf
	v_mov_b32_dpp v183, v135 row_shr:2 row_mask:0xf bank_mask:0xf
	v_fma_f32 v179, v147, v183, v163
	v_fmac_f32_e32 v179, v151, v182
	v_fmac_f32_e32 v179, v135, v155
	v_mul_f32_e32 v176, v177, v176
	v_mul_f32_e32 v179, v179, v176
	v_or_b32_e32 v176, 32, v210
	v_mad_i64_i32 v[176:177], s[54:55], v176, s77, v[194:195]
	v_lshl_add_u64 v[176:177], v[176:177], 0, v[198:199]
	v_cvt_pk_bf16_f32 v201, v178, v179
	v_mov_b32_dpp v179, v140 row_ror:2 row_mask:0xf bank_mask:0xf
	s_nop 0
	v_mov_b32_dpp v178, v140 row_ror:1 row_mask:0xf bank_mask:0xf
	v_mov_b32_dpp v179, v136 row_shr:2 row_mask:0xf bank_mask:0xf
	v_fma_f32 v179, v164, v179, v156
	v_mov_b32_dpp v178, v136 row_shr:1 row_mask:0xf bank_mask:0xf
	v_fmac_f32_e32 v179, v168, v178
	v_fmac_f32_e32 v179, v136, v172
	v_mul_f32_e32 v136, 0xbfb8aa3b, v179
	v_exp_f32_e32 v136, v136
	s_nop 0
	v_mov_b32_dpp v140, v132 row_ror:1 row_mask:0xf bank_mask:0xf
	v_mov_b32_dpp v178, v132 row_ror:2 row_mask:0xf bank_mask:0xf
	v_add_f32_e32 v132, 1.0, v136
	v_rcp_f32_e32 v132, v132
	v_mov_b32_dpp v178, v128 row_shr:2 row_mask:0xf bank_mask:0xf
	v_mov_b32_dpp v140, v128 row_shr:1 row_mask:0xf bank_mask:0xf
	v_fma_f32 v136, v144, v178, v160
	v_fmac_f32_e32 v136, v148, v140
	v_fmac_f32_e32 v136, v128, v152
	v_mul_f32_e32 v128, v179, v132
	v_mul_f32_e32 v132, v136, v128
	v_mov_b32_dpp v136, v141 row_ror:2 row_mask:0xf bank_mask:0xf
	v_mov_b32_dpp v128, v141 row_ror:1 row_mask:0xf bank_mask:0xf
	v_mov_b32_dpp v140, v133 row_ror:1 row_mask:0xf bank_mask:0xf
	v_mov_b32_dpp v136, v137 row_shr:2 row_mask:0xf bank_mask:0xf
	v_mov_b32_dpp v128, v137 row_shr:1 row_mask:0xf bank_mask:0xf
	v_fma_f32 v136, v165, v136, v157
	v_fmac_f32_e32 v136, v169, v128
	v_fmac_f32_e32 v136, v137, v173
	v_mul_f32_e32 v128, 0xbfb8aa3b, v136
	v_exp_f32_e32 v128, v128
	v_mov_b32_dpp v140, v129 row_shr:1 row_mask:0xf bank_mask:0xf
	v_add_f32_e32 v128, 1.0, v128
	v_mov_b32_dpp v137, v133 row_ror:2 row_mask:0xf bank_mask:0xf
	v_rcp_f32_e32 v128, v128
	s_nop 0
	v_mov_b32_dpp v137, v129 row_shr:2 row_mask:0xf bank_mask:0xf
	v_fma_f32 v133, v145, v137, v161
	v_fmac_f32_e32 v133, v149, v140
	v_fmac_f32_e32 v133, v129, v153
	v_mul_f32_e32 v128, v136, v128
	v_mul_f32_e32 v133, v133, v128
	v_mov_b32_dpp v129, v142 row_ror:2 row_mask:0xf bank_mask:0xf
	v_mov_b32_dpp v128, v142 row_ror:1 row_mask:0xf bank_mask:0xf
	v_mov_b32_dpp v129, v138 row_shr:2 row_mask:0xf bank_mask:0xf
	v_fma_f32 v129, v166, v129, v158
	v_mov_b32_dpp v128, v138 row_shr:1 row_mask:0xf bank_mask:0xf
	v_fmac_f32_e32 v129, v170, v128
	v_fmac_f32_e32 v129, v138, v174
	v_mul_f32_e32 v128, 0xbfb8aa3b, v129
	v_exp_f32_e32 v128, v128
	v_mov_b32_dpp v137, v134 row_ror:2 row_mask:0xf bank_mask:0xf
	v_add_f32_e32 v128, 1.0, v128
	v_rcp_f32_e32 v128, v128
	v_mov_b32_dpp v136, v134 row_ror:1 row_mask:0xf bank_mask:0xf
	v_mov_b32_dpp v137, v130 row_shr:2 row_mask:0xf bank_mask:0xf
	v_fma_f32 v134, v146, v137, v162
	v_mov_b32_dpp v136, v130 row_shr:1 row_mask:0xf bank_mask:0xf
	v_fmac_f32_e32 v134, v150, v136
	v_fmac_f32_e32 v134, v130, v154
	v_mul_f32_e32 v128, v129, v128
	v_mul_f32_e32 v130, v134, v128
	v_mov_b32_dpp v129, v143 row_ror:2 row_mask:0xf bank_mask:0xf
	v_mov_b32_dpp v128, v143 row_ror:1 row_mask:0xf bank_mask:0xf
	v_mov_b32_dpp v129, v139 row_shr:2 row_mask:0xf bank_mask:0xf
	v_fma_f32 v129, v167, v129, v159
	v_mov_b32_dpp v128, v139 row_shr:1 row_mask:0xf bank_mask:0xf
	v_fmac_f32_e32 v129, v171, v128
	v_fmac_f32_e32 v129, v139, v175
	v_mul_f32_e32 v128, 0xbfb8aa3b, v129
	v_exp_f32_e32 v128, v128
	v_mov_b32_dpp v136, v135 row_ror:2 row_mask:0xf bank_mask:0xf
	v_add_f32_e32 v128, 1.0, v128
	v_rcp_f32_e32 v128, v128
	v_mov_b32_dpp v134, v135 row_ror:1 row_mask:0xf bank_mask:0xf
	v_mov_b32_dpp v136, v131 row_shr:2 row_mask:0xf bank_mask:0xf
	v_fma_f32 v135, v147, v136, v163
	v_mov_b32_dpp v134, v131 row_shr:1 row_mask:0xf bank_mask:0xf
	v_fmac_f32_e32 v135, v151, v134
	v_fmac_f32_e32 v135, v131, v155
	v_mul_f32_e32 v128, v129, v128
	v_mul_f32_e32 v131, v135, v128
	v_or_b32_e32 v128, 48, v210
	v_mad_i64_i32 v[128:129], s[54:55], v128, s77, v[194:195]
	v_lshl_add_u64 v[134:135], v[128:129], 0, v[198:199]
	v_cvt_pk_bf16_f32 v226, v132, v133
	v_cvt_pk_bf16_f32 v227, v130, v131
	v_mov_b32_e32 v194, 0
	v_mov_b32_e32 v195, 0
	v_mov_b32_e32 v130, 0
	v_mov_b32_e32 v131, 0
	v_mov_b32_e32 v132, 0
	v_mov_b32_e32 v133, 0
	s_and_saveexec_b64 s[54:55], s[4:5]
	s_cbranch_execz .LBB0_717
	ds_read_b128 v[192:195], v233
	ds_read_b128 v[130:133], v232
.LBB0_717:
	s_or_b64 exec, exec, s[54:55]
	s_waitcnt lgkmcnt(1)
	v_mov_b32_dpp v137, v192 row_ror:2 row_mask:0xf bank_mask:0xf
	v_mov_b32_dpp v136, v192 row_ror:1 row_mask:0xf bank_mask:0xf
	v_mov_b32_dpp v137, v124 row_shr:2 row_mask:0xf bank_mask:0xf
	v_mov_b32_dpp v136, v124 row_shr:1 row_mask:0xf bank_mask:0xf
	v_fma_f32 v137, v164, v137, v156
	v_fmac_f32_e32 v137, v168, v136
	v_fmac_f32_e32 v137, v124, v172
	v_mul_f32_e32 v136, 0xbfb8aa3b, v137
	v_exp_f32_e32 v136, v136
	s_waitcnt lgkmcnt(0)
	v_mov_b32_dpp v138, v130 row_ror:1 row_mask:0xf bank_mask:0xf
	v_mov_b32_dpp v139, v130 row_ror:2 row_mask:0xf bank_mask:0xf
	v_add_u32_e32 v129, 0x80, v210
	v_add_f32_e32 v130, 1.0, v136
	v_rcp_f32_e32 v130, v130
	v_mov_b32_dpp v139, v120 row_shr:2 row_mask:0xf bank_mask:0xf
	v_mov_b32_dpp v138, v120 row_shr:1 row_mask:0xf bank_mask:0xf
	v_fma_f32 v136, v144, v139, v160
	v_fmac_f32_e32 v136, v148, v138
	v_fmac_f32_e32 v136, v120, v152
	v_mul_f32_e32 v130, v137, v130
	v_mul_f32_e32 v136, v136, v130
	v_mov_b32_dpp v137, v193 row_ror:2 row_mask:0xf bank_mask:0xf
	v_mov_b32_dpp v130, v193 row_ror:1 row_mask:0xf bank_mask:0xf
	v_mov_b32_dpp v137, v125 row_shr:2 row_mask:0xf bank_mask:0xf
	v_fma_f32 v137, v165, v137, v157
	v_mov_b32_dpp v130, v125 row_shr:1 row_mask:0xf bank_mask:0xf
	v_fmac_f32_e32 v137, v169, v130
	v_fmac_f32_e32 v137, v125, v173
	v_mul_f32_e32 v130, 0xbfb8aa3b, v137
	v_exp_f32_e32 v130, v130
	v_mov_b32_dpp v139, v131 row_ror:2 row_mask:0xf bank_mask:0xf
	v_mov_b32_e32 v128, 0
	v_add_f32_e32 v130, 1.0, v130
	v_rcp_f32_e32 v130, v130
	v_mov_b32_dpp v138, v131 row_ror:1 row_mask:0xf bank_mask:0xf
	v_mov_b32_dpp v139, v121 row_shr:2 row_mask:0xf bank_mask:0xf
	v_fma_f32 v131, v145, v139, v161
	v_mov_b32_dpp v138, v121 row_shr:1 row_mask:0xf bank_mask:0xf
	v_fmac_f32_e32 v131, v149, v138
	v_fmac_f32_e32 v131, v121, v153
	v_mul_f32_e32 v130, v137, v130
	v_mul_f32_e32 v137, v131, v130
	v_mov_b32_dpp v131, v194 row_ror:2 row_mask:0xf bank_mask:0xf
	v_mov_b32_dpp v130, v194 row_ror:1 row_mask:0xf bank_mask:0xf
	v_mov_b32_dpp v131, v126 row_shr:2 row_mask:0xf bank_mask:0xf
	v_mov_b32_dpp v130, v126 row_shr:1 row_mask:0xf bank_mask:0xf
	v_fma_f32 v131, v166, v131, v158
	v_fmac_f32_e32 v131, v170, v130
	v_fmac_f32_e32 v131, v126, v174
	v_mul_f32_e32 v130, 0xbfb8aa3b, v131
	v_exp_f32_e32 v130, v130
	v_mov_b32_dpp v139, v132 row_ror:2 row_mask:0xf bank_mask:0xf
	v_mov_b32_dpp v138, v132 row_ror:1 row_mask:0xf bank_mask:0xf
	v_add_f32_e32 v130, 1.0, v130
	v_rcp_f32_e32 v130, v130
	v_mov_b32_dpp v139, v122 row_shr:2 row_mask:0xf bank_mask:0xf
	v_mov_b32_dpp v138, v122 row_shr:1 row_mask:0xf bank_mask:0xf
	v_fma_f32 v132, v146, v139, v162
	v_fmac_f32_e32 v132, v150, v138
	v_fmac_f32_e32 v132, v122, v154
	v_mul_f32_e32 v130, v131, v130
	v_mul_f32_e32 v138, v132, v130
	v_mov_b32_dpp v131, v195 row_ror:2 row_mask:0xf bank_mask:0xf
	v_mov_b32_dpp v130, v195 row_ror:1 row_mask:0xf bank_mask:0xf
	v_mov_b32_dpp v131, v127 row_shr:2 row_mask:0xf bank_mask:0xf
	v_fma_f32 v131, v167, v131, v159
	v_mov_b32_dpp v130, v127 row_shr:1 row_mask:0xf bank_mask:0xf
	v_fmac_f32_e32 v131, v171, v130
	v_fmac_f32_e32 v131, v127, v175
	v_mul_f32_e32 v130, 0xbfb8aa3b, v131
	v_exp_f32_e32 v130, v130
	v_mov_b32_dpp v139, v133 row_ror:2 row_mask:0xf bank_mask:0xf
	v_add_f32_e32 v130, 1.0, v130
	v_rcp_f32_e32 v130, v130
	v_mov_b32_dpp v132, v133 row_ror:1 row_mask:0xf bank_mask:0xf
	v_mov_b32_dpp v139, v123 row_shr:2 row_mask:0xf bank_mask:0xf
	v_fma_f32 v133, v147, v139, v163
	v_mov_b32_dpp v132, v123 row_shr:1 row_mask:0xf bank_mask:0xf
	v_fmac_f32_e32 v133, v151, v132
	v_fmac_f32_e32 v133, v123, v155
	v_mul_f32_e32 v130, v131, v130
	v_mul_f32_e32 v139, v133, v130
	v_mov_b64_e32 v[130:131], s[12:13]
	v_mad_i64_i32 v[132:133], s[54:55], v129, s77, v[130:131]
	v_lshl_add_u64 v[132:133], v[132:133], 0, v[198:199]
	v_cvt_pk_bf16_f32 v186, v136, v137
	v_cvt_pk_bf16_f32 v187, v138, v139
	v_mov_b32_dpp v136, v124 row_ror:2 row_mask:0xf bank_mask:0xf
	v_mov_b32_dpp v129, v124 row_ror:1 row_mask:0xf bank_mask:0xf
	v_mov_b32_dpp v136, v116 row_shr:2 row_mask:0xf bank_mask:0xf
	v_fma_f32 v136, v164, v136, v156
	v_mov_b32_dpp v129, v116 row_shr:1 row_mask:0xf bank_mask:0xf
	v_fmac_f32_e32 v136, v168, v129
	v_fmac_f32_e32 v136, v116, v172
	v_mul_f32_e32 v129, 0xbfb8aa3b, v136
	v_exp_f32_e32 v129, v129
	v_mov_b32_dpp v137, v120 row_ror:2 row_mask:0xf bank_mask:0xf
	s_nop 0
	v_mov_b32_dpp v124, v120 row_ror:1 row_mask:0xf bank_mask:0xf
	v_add_f32_e32 v120, 1.0, v129
	v_rcp_f32_e32 v120, v120
	v_mov_b32_dpp v137, v112 row_shr:2 row_mask:0xf bank_mask:0xf
	v_mov_b32_dpp v124, v112 row_shr:1 row_mask:0xf bank_mask:0xf
	v_fma_f32 v129, v144, v137, v160
	v_fmac_f32_e32 v129, v148, v124
	v_fmac_f32_e32 v129, v112, v152
	v_mul_f32_e32 v120, v136, v120
	v_mul_f32_e32 v124, v129, v120
	v_mov_b32_dpp v129, v125 row_ror:2 row_mask:0xf bank_mask:0xf
	v_mov_b32_dpp v120, v125 row_ror:1 row_mask:0xf bank_mask:0xf
	v_mov_b32_dpp v129, v117 row_shr:2 row_mask:0xf bank_mask:0xf
	v_mov_b32_dpp v120, v117 row_shr:1 row_mask:0xf bank_mask:0xf
	v_fma_f32 v129, v165, v129, v157
	v_fmac_f32_e32 v129, v169, v120
	v_fmac_f32_e32 v129, v117, v173
	v_mul_f32_e32 v120, 0xbfb8aa3b, v129
	v_exp_f32_e32 v120, v120
	v_mov_b32_dpp v136, v121 row_ror:2 row_mask:0xf bank_mask:0xf
	v_mov_b32_dpp v125, v121 row_ror:1 row_mask:0xf bank_mask:0xf
	v_add_f32_e32 v120, 1.0, v120
	v_rcp_f32_e32 v120, v120
	v_mov_b32_dpp v136, v113 row_shr:2 row_mask:0xf bank_mask:0xf
	v_mov_b32_dpp v125, v113 row_shr:1 row_mask:0xf bank_mask:0xf
	v_fma_f32 v121, v145, v136, v161
	v_fmac_f32_e32 v121, v149, v125
	v_fmac_f32_e32 v121, v113, v153
	v_mul_f32_e32 v120, v129, v120
	v_mul_f32_e32 v125, v121, v120
	v_mov_b32_dpp v121, v126 row_ror:2 row_mask:0xf bank_mask:0xf
	v_mov_b32_dpp v120, v126 row_ror:1 row_mask:0xf bank_mask:0xf
	v_mov_b32_dpp v121, v118 row_shr:2 row_mask:0xf bank_mask:0xf
	v_mov_b32_dpp v120, v118 row_shr:1 row_mask:0xf bank_mask:0xf
	v_fma_f32 v121, v166, v121, v158
	v_fmac_f32_e32 v121, v170, v120
	v_fmac_f32_e32 v121, v118, v174
	v_mul_f32_e32 v120, 0xbfb8aa3b, v121
	v_exp_f32_e32 v120, v120
	v_mov_b32_dpp v129, v122 row_ror:2 row_mask:0xf bank_mask:0xf
	v_mov_b32_dpp v126, v122 row_ror:1 row_mask:0xf bank_mask:0xf
	v_cvt_pk_bf16_f32 v188, v124, v125
	v_add_f32_e32 v120, 1.0, v120
	v_rcp_f32_e32 v120, v120
	v_mov_b32_dpp v129, v114 row_shr:2 row_mask:0xf bank_mask:0xf
	v_mov_b32_dpp v126, v114 row_shr:1 row_mask:0xf bank_mask:0xf
	v_fma_f32 v122, v146, v129, v162
	v_fmac_f32_e32 v122, v150, v126
	v_fmac_f32_e32 v122, v114, v154
	v_mul_f32_e32 v120, v121, v120
	v_mul_f32_e32 v122, v122, v120
	v_mov_b32_dpp v121, v127 row_ror:2 row_mask:0xf bank_mask:0xf
	v_mov_b32_dpp v120, v127 row_ror:1 row_mask:0xf bank_mask:0xf
	v_mov_b32_dpp v121, v119 row_shr:2 row_mask:0xf bank_mask:0xf
	v_fma_f32 v121, v167, v121, v159
	v_mov_b32_dpp v120, v119 row_shr:1 row_mask:0xf bank_mask:0xf
	v_fmac_f32_e32 v121, v171, v120
	v_fmac_f32_e32 v121, v119, v175
	v_mul_f32_e32 v120, 0xbfb8aa3b, v121
	v_exp_f32_e32 v120, v120
	v_mov_b32_dpp v126, v123 row_ror:1 row_mask:0xf bank_mask:0xf
	v_add_f32_e32 v120, 1.0, v120
	v_mov_b32_dpp v127, v123 row_ror:2 row_mask:0xf bank_mask:0xf
	v_rcp_f32_e32 v120, v120
	v_mov_b32_dpp v126, v115 row_shr:1 row_mask:0xf bank_mask:0xf
	v_mov_b32_dpp v127, v115 row_shr:2 row_mask:0xf bank_mask:0xf
	v_fma_f32 v123, v147, v127, v163
	v_fmac_f32_e32 v123, v151, v126
	v_fmac_f32_e32 v123, v115, v155
	v_mul_f32_e32 v120, v121, v120
	v_mul_f32_e32 v123, v123, v120
	v_add_u32_e32 v120, 0x90, v210
	v_mad_i64_i32 v[120:121], s[54:55], v120, s77, v[130:131]
	v_lshl_add_u64 v[120:121], v[120:121], 0, v[198:199]
	v_cvt_pk_bf16_f32 v189, v122, v123
	v_mov_b32_dpp v123, v116 row_ror:2 row_mask:0xf bank_mask:0xf
	v_mov_b32_dpp v122, v116 row_ror:1 row_mask:0xf bank_mask:0xf
	v_mov_b32_dpp v123, v108 row_shr:2 row_mask:0xf bank_mask:0xf
	v_fma_f32 v123, v164, v123, v156
	v_mov_b32_dpp v122, v108 row_shr:1 row_mask:0xf bank_mask:0xf
	v_fmac_f32_e32 v123, v168, v122
	v_fmac_f32_e32 v123, v108, v172
	v_mul_f32_e32 v122, 0xbfb8aa3b, v123
	v_exp_f32_e32 v122, v122
	v_mov_b32_dpp v124, v112 row_ror:2 row_mask:0xf bank_mask:0xf
	s_nop 0
	v_mov_b32_dpp v116, v112 row_ror:1 row_mask:0xf bank_mask:0xf
	v_add_f32_e32 v112, 1.0, v122
	v_rcp_f32_e32 v112, v112
	v_mov_b32_dpp v124, v100 row_shr:2 row_mask:0xf bank_mask:0xf
	v_mov_b32_dpp v116, v100 row_shr:1 row_mask:0xf bank_mask:0xf
	v_fma_f32 v122, v144, v124, v160
	v_fmac_f32_e32 v122, v148, v116
	v_fmac_f32_e32 v122, v100, v152
	v_mul_f32_e32 v112, v123, v112
	v_mul_f32_e32 v116, v122, v112
	v_mov_b32_dpp v122, v117 row_ror:2 row_mask:0xf bank_mask:0xf
	v_mov_b32_dpp v112, v117 row_ror:1 row_mask:0xf bank_mask:0xf
	v_mov_b32_dpp v122, v109 row_shr:2 row_mask:0xf bank_mask:0xf
	v_mov_b32_dpp v112, v109 row_shr:1 row_mask:0xf bank_mask:0xf
	v_fma_f32 v122, v165, v122, v157
	v_fmac_f32_e32 v122, v169, v112
	v_fmac_f32_e32 v122, v109, v173
	v_mul_f32_e32 v112, 0xbfb8aa3b, v122
	v_exp_f32_e32 v112, v112
	v_mov_b32_dpp v123, v113 row_ror:2 row_mask:0xf bank_mask:0xf
	v_mov_b32_dpp v117, v113 row_ror:1 row_mask:0xf bank_mask:0xf
	v_add_f32_e32 v112, 1.0, v112
	v_rcp_f32_e32 v112, v112
	v_mov_b32_dpp v123, v101 row_shr:2 row_mask:0xf bank_mask:0xf
	v_mov_b32_dpp v117, v101 row_shr:1 row_mask:0xf bank_mask:0xf
	v_fma_f32 v113, v145, v123, v161
	v_fmac_f32_e32 v113, v149, v117
	v_fmac_f32_e32 v113, v101, v153
	v_mul_f32_e32 v112, v122, v112
	v_mul_f32_e32 v117, v113, v112
	v_mov_b32_dpp v113, v118 row_ror:2 row_mask:0xf bank_mask:0xf
	v_mov_b32_dpp v112, v118 row_ror:1 row_mask:0xf bank_mask:0xf
	v_mov_b32_dpp v113, v110 row_shr:2 row_mask:0xf bank_mask:0xf
	v_mov_b32_dpp v112, v110 row_shr:1 row_mask:0xf bank_mask:0xf
	v_fma_f32 v113, v166, v113, v158
	v_fmac_f32_e32 v113, v170, v112
	v_fmac_f32_e32 v113, v110, v174
	v_mul_f32_e32 v112, 0xbfb8aa3b, v113
	v_exp_f32_e32 v112, v112
	v_mov_b32_dpp v122, v114 row_ror:2 row_mask:0xf bank_mask:0xf
	v_mov_b32_dpp v118, v114 row_ror:1 row_mask:0xf bank_mask:0xf
	v_cvt_pk_bf16_f32 v190, v116, v117
	v_add_f32_e32 v112, 1.0, v112
	v_rcp_f32_e32 v112, v112
	v_mov_b32_dpp v122, v102 row_shr:2 row_mask:0xf bank_mask:0xf
	v_mov_b32_dpp v118, v102 row_shr:1 row_mask:0xf bank_mask:0xf
	v_fma_f32 v114, v146, v122, v162
	v_fmac_f32_e32 v114, v150, v118
	v_fmac_f32_e32 v114, v102, v154
	v_mul_f32_e32 v112, v113, v112
	v_mul_f32_e32 v114, v114, v112
	v_mov_b32_dpp v113, v119 row_ror:2 row_mask:0xf bank_mask:0xf
	v_mov_b32_dpp v112, v119 row_ror:1 row_mask:0xf bank_mask:0xf
	v_mov_b32_dpp v113, v111 row_shr:2 row_mask:0xf bank_mask:0xf
	v_fma_f32 v113, v167, v113, v159
	v_mov_b32_dpp v112, v111 row_shr:1 row_mask:0xf bank_mask:0xf
	v_fmac_f32_e32 v113, v171, v112
	v_fmac_f32_e32 v113, v111, v175
	v_mul_f32_e32 v112, 0xbfb8aa3b, v113
	v_exp_f32_e32 v112, v112
	v_mov_b32_dpp v118, v115 row_ror:1 row_mask:0xf bank_mask:0xf
	v_add_f32_e32 v112, 1.0, v112
	v_mov_b32_dpp v119, v115 row_ror:2 row_mask:0xf bank_mask:0xf
	v_rcp_f32_e32 v112, v112
	v_mov_b32_dpp v118, v103 row_shr:1 row_mask:0xf bank_mask:0xf
	v_mov_b32_dpp v119, v103 row_shr:2 row_mask:0xf bank_mask:0xf
	v_fma_f32 v115, v147, v119, v163
	v_fmac_f32_e32 v115, v151, v118
	v_fmac_f32_e32 v115, v103, v155
	v_mul_f32_e32 v112, v113, v112
	v_mul_f32_e32 v115, v115, v112
	v_add_u32_e32 v112, 0xa0, v210
	v_mad_i64_i32 v[112:113], s[54:55], v112, s77, v[130:131]
	v_lshl_add_u64 v[112:113], v[112:113], 0, v[198:199]
	v_cvt_pk_bf16_f32 v191, v114, v115
	v_mov_b32_dpp v115, v108 row_ror:2 row_mask:0xf bank_mask:0xf
	s_nop 0
	v_mov_b32_dpp v114, v108 row_ror:1 row_mask:0xf bank_mask:0xf
	v_mov_b32_dpp v115, v104 row_shr:2 row_mask:0xf bank_mask:0xf
	v_fma_f32 v115, v164, v115, v156
	v_mov_b32_dpp v114, v104 row_shr:1 row_mask:0xf bank_mask:0xf
	v_fmac_f32_e32 v115, v168, v114
	v_fmac_f32_e32 v115, v104, v172
	v_mul_f32_e32 v104, 0xbfb8aa3b, v115
	v_exp_f32_e32 v104, v104
	s_nop 0
	v_mov_b32_dpp v108, v100 row_ror:1 row_mask:0xf bank_mask:0xf
	v_mov_b32_dpp v114, v100 row_ror:2 row_mask:0xf bank_mask:0xf
	v_add_f32_e32 v100, 1.0, v104
	v_rcp_f32_e32 v100, v100
	v_mov_b32_dpp v114, v96 row_shr:2 row_mask:0xf bank_mask:0xf
	v_mov_b32_dpp v108, v96 row_shr:1 row_mask:0xf bank_mask:0xf
	v_fma_f32 v104, v144, v114, v160
	v_fmac_f32_e32 v104, v148, v108
	v_fmac_f32_e32 v104, v96, v152
	v_mul_f32_e32 v96, v115, v100
	v_mul_f32_e32 v100, v104, v96
	v_mov_b32_dpp v104, v109 row_ror:2 row_mask:0xf bank_mask:0xf
	v_mov_b32_dpp v96, v109 row_ror:1 row_mask:0xf bank_mask:0xf
	v_mov_b32_dpp v108, v101 row_ror:1 row_mask:0xf bank_mask:0xf
	v_mov_b32_dpp v104, v105 row_shr:2 row_mask:0xf bank_mask:0xf
	v_mov_b32_dpp v96, v105 row_shr:1 row_mask:0xf bank_mask:0xf
	v_fma_f32 v104, v165, v104, v157
	v_fmac_f32_e32 v104, v169, v96
	v_fmac_f32_e32 v104, v105, v173
	v_mul_f32_e32 v96, 0xbfb8aa3b, v104
	v_exp_f32_e32 v96, v96
	v_mov_b32_dpp v108, v97 row_shr:1 row_mask:0xf bank_mask:0xf
	v_add_f32_e32 v96, 1.0, v96
	v_mov_b32_dpp v105, v101 row_ror:2 row_mask:0xf bank_mask:0xf
	v_rcp_f32_e32 v96, v96
	s_nop 0
	v_mov_b32_dpp v105, v97 row_shr:2 row_mask:0xf bank_mask:0xf
	v_fma_f32 v101, v145, v105, v161
	v_fmac_f32_e32 v101, v149, v108
	v_fmac_f32_e32 v101, v97, v153
	v_mul_f32_e32 v96, v104, v96
	v_mul_f32_e32 v101, v101, v96
	v_mov_b32_dpp v97, v110 row_ror:2 row_mask:0xf bank_mask:0xf
	v_mov_b32_dpp v96, v110 row_ror:1 row_mask:0xf bank_mask:0xf
	v_mov_b32_dpp v97, v106 row_shr:2 row_mask:0xf bank_mask:0xf
	v_fma_f32 v97, v166, v97, v158
	v_mov_b32_dpp v96, v106 row_shr:1 row_mask:0xf bank_mask:0xf
	v_fmac_f32_e32 v97, v170, v96
	v_fmac_f32_e32 v97, v106, v174
	v_mul_f32_e32 v96, 0xbfb8aa3b, v97
	v_exp_f32_e32 v96, v96
	v_mov_b32_dpp v105, v102 row_ror:2 row_mask:0xf bank_mask:0xf
	v_add_f32_e32 v96, 1.0, v96
	v_rcp_f32_e32 v96, v96
	v_mov_b32_dpp v104, v102 row_ror:1 row_mask:0xf bank_mask:0xf
	v_mov_b32_dpp v105, v98 row_shr:2 row_mask:0xf bank_mask:0xf
	v_fma_f32 v102, v146, v105, v162
	v_mov_b32_dpp v104, v98 row_shr:1 row_mask:0xf bank_mask:0xf
	v_fmac_f32_e32 v102, v150, v104
	v_fmac_f32_e32 v102, v98, v154
	v_mul_f32_e32 v96, v97, v96
	v_mul_f32_e32 v98, v102, v96
	v_mov_b32_dpp v97, v111 row_ror:2 row_mask:0xf bank_mask:0xf
	v_mov_b32_dpp v96, v111 row_ror:1 row_mask:0xf bank_mask:0xf
	v_mov_b32_dpp v97, v107 row_shr:2 row_mask:0xf bank_mask:0xf
	v_fmac_f32_e32 v159, v167, v97
	v_mov_b32_dpp v96, v107 row_shr:1 row_mask:0xf bank_mask:0xf
	v_fmac_f32_e32 v159, v171, v96
	v_fmac_f32_e32 v159, v107, v175
	v_mul_f32_e32 v96, 0xbfb8aa3b, v159
	v_exp_f32_e32 v96, v96
	v_mov_b32_dpp v102, v103 row_ror:1 row_mask:0xf bank_mask:0xf
	v_add_f32_e32 v96, 1.0, v96
	v_mov_b32_dpp v97, v103 row_ror:2 row_mask:0xf bank_mask:0xf
	v_rcp_f32_e32 v96, v96
	v_mov_b32_dpp v102, v99 row_shr:1 row_mask:0xf bank_mask:0xf
	v_mov_b32_dpp v97, v99 row_shr:2 row_mask:0xf bank_mask:0xf
	v_fmac_f32_e32 v163, v147, v97
	v_fmac_f32_e32 v163, v151, v102
	v_fmac_f32_e32 v163, v99, v155
	v_mul_f32_e32 v96, v159, v96
	v_mul_f32_e32 v99, v163, v96
	v_add_u32_e32 v96, 0xb0, v210
	v_mad_i64_i32 v[96:97], s[54:55], v96, s77, v[130:131]
	v_lshl_add_u64 v[104:105], v[96:97], 0, v[198:199]
	v_cvt_pk_bf16_f32 v192, v100, v101
	v_cvt_pk_bf16_f32 v193, v98, v99
	v_mov_b32_e32 v100, 0
	v_mov_b32_e32 v101, 0
	v_mov_b32_e32 v102, 0
	v_mov_b32_e32 v103, 0
	v_mov_b32_e32 v96, 0
	v_mov_b32_e32 v97, 0
	v_mov_b32_e32 v98, 0
	v_mov_b32_e32 v99, 0
	s_and_saveexec_b64 s[54:55], s[24:25]
	s_cbranch_execz .LBB0_719
	ds_read_b128 v[100:103], v235
	ds_read_b128 v[96:99], v234
.LBB0_719:
	s_or_b64 exec, exec, s[54:55]
	s_waitcnt lgkmcnt(1)
	v_mov_b32_dpp v107, v100 row_ror:2 row_mask:0xf bank_mask:0xf
	v_mov_b32_dpp v106, v100 row_ror:1 row_mask:0xf bank_mask:0xf
	v_mov_b32_dpp v107, v92 row_shr:2 row_mask:0xf bank_mask:0xf
	v_mov_b32_dpp v106, v92 row_shr:1 row_mask:0xf bank_mask:0xf
	v_fma_f32 v107, v68, v107, v60
	v_fmac_f32_e32 v107, v72, v106
	v_fmac_f32_e32 v107, v92, v76
	v_mul_f32_e32 v106, 0xbfb8aa3b, v107
	v_exp_f32_e32 v106, v106
	s_waitcnt lgkmcnt(0)
	v_mov_b32_dpp v100, v96 row_ror:1 row_mask:0xf bank_mask:0xf
	v_mov_b32_dpp v108, v96 row_ror:2 row_mask:0xf bank_mask:0xf
	v_mov_b32_e32 v129, 0
	v_add_f32_e32 v96, 1.0, v106
	v_rcp_f32_e32 v96, v96
	v_mov_b32_dpp v108, v88 row_shr:2 row_mask:0xf bank_mask:0xf
	v_mov_b32_dpp v100, v88 row_shr:1 row_mask:0xf bank_mask:0xf
	v_fma_f32 v106, v48, v108, v64
	v_fmac_f32_e32 v106, v52, v100
	v_fmac_f32_e32 v106, v88, v56
	v_mul_f32_e32 v96, v107, v96
	v_mul_f32_e32 v96, v106, v96
	v_mov_b32_dpp v106, v101 row_ror:2 row_mask:0xf bank_mask:0xf
	v_mov_b32_dpp v100, v101 row_ror:1 row_mask:0xf bank_mask:0xf
	v_mov_b32_dpp v106, v93 row_shr:2 row_mask:0xf bank_mask:0xf
	v_mov_b32_dpp v100, v93 row_shr:1 row_mask:0xf bank_mask:0xf
	v_fma_f32 v106, v69, v106, v61
	v_fmac_f32_e32 v106, v73, v100
	v_fmac_f32_e32 v106, v93, v77
	v_mul_f32_e32 v100, 0xbfb8aa3b, v106
	v_exp_f32_e32 v100, v100
	v_mov_b32_dpp v101, v97 row_ror:1 row_mask:0xf bank_mask:0xf
	v_mov_b32_dpp v107, v97 row_ror:2 row_mask:0xf bank_mask:0xf
	v_mov_b32_e32 v130, 0
	v_add_f32_e32 v97, 1.0, v100
	v_rcp_f32_e32 v97, v97
	v_mov_b32_dpp v107, v89 row_shr:2 row_mask:0xf bank_mask:0xf
	v_mov_b32_dpp v101, v89 row_shr:1 row_mask:0xf bank_mask:0xf
	v_fma_f32 v100, v49, v107, v65
	v_fmac_f32_e32 v100, v53, v101
	v_fmac_f32_e32 v100, v89, v57
	v_mul_f32_e32 v97, v106, v97
	v_mul_f32_e32 v97, v100, v97
	v_mov_b32_dpp v101, v102 row_ror:2 row_mask:0xf bank_mask:0xf
	v_mov_b32_dpp v100, v102 row_ror:1 row_mask:0xf bank_mask:0xf
	v_mov_b32_dpp v101, v94 row_shr:2 row_mask:0xf bank_mask:0xf
	v_fma_f32 v101, v70, v101, v62
	v_mov_b32_dpp v100, v94 row_shr:1 row_mask:0xf bank_mask:0xf
	v_fmac_f32_e32 v101, v74, v100
	v_fmac_f32_e32 v101, v94, v78
	v_mul_f32_e32 v100, 0xbfb8aa3b, v101
	v_exp_f32_e32 v100, v100
	v_mov_b32_dpp v106, v98 row_ror:2 row_mask:0xf bank_mask:0xf
	v_cvt_pk_bf16_f32 v146, v96, v97
	v_mov_b32_dpp v102, v98 row_ror:1 row_mask:0xf bank_mask:0xf
	v_add_f32_e32 v98, 1.0, v100
	v_rcp_f32_e32 v98, v98
	v_mov_b32_dpp v106, v90 row_shr:2 row_mask:0xf bank_mask:0xf
	v_mov_b32_dpp v102, v90 row_shr:1 row_mask:0xf bank_mask:0xf
	v_fma_f32 v100, v50, v106, v66
	v_fmac_f32_e32 v100, v54, v102
	v_fmac_f32_e32 v100, v90, v58
	v_mul_f32_e32 v98, v101, v98
	v_mul_f32_e32 v98, v100, v98
	v_mov_b32_dpp v101, v103 row_ror:2 row_mask:0xf bank_mask:0xf
	v_mov_b32_dpp v100, v103 row_ror:1 row_mask:0xf bank_mask:0xf
	v_mov_b32_dpp v101, v95 row_shr:2 row_mask:0xf bank_mask:0xf
	v_fma_f32 v101, v71, v101, v63
	v_mov_b32_dpp v100, v95 row_shr:1 row_mask:0xf bank_mask:0xf
	v_fmac_f32_e32 v101, v75, v100
	v_fmac_f32_e32 v101, v95, v79
	v_mul_f32_e32 v100, 0xbfb8aa3b, v101
	v_exp_f32_e32 v100, v100
	v_mov_b32_dpp v102, v99 row_ror:1 row_mask:0xf bank_mask:0xf
	v_mov_b32_dpp v103, v99 row_ror:2 row_mask:0xf bank_mask:0xf
	v_add_f32_e32 v99, 1.0, v100
	v_rcp_f32_e32 v99, v99
	v_mov_b32_dpp v103, v91 row_shr:2 row_mask:0xf bank_mask:0xf
	v_mov_b32_dpp v102, v91 row_shr:1 row_mask:0xf bank_mask:0xf
	v_fma_f32 v100, v51, v103, v67
	v_fmac_f32_e32 v100, v55, v102
	v_fmac_f32_e32 v100, v91, v59
	v_mul_f32_e32 v99, v101, v99
	v_mul_f32_e32 v99, v100, v99
	v_cvt_pk_bf16_f32 v147, v98, v99
	v_mov_b32_e32 v144, v244
	v_mov_b32_e32 v145, v245
	global_store_dwordx4 v[196:197], v[144:147], off
	v_mov_b32_dpp v97, v92 row_ror:2 row_mask:0xf bank_mask:0xf
	v_mov_b32_dpp v96, v92 row_ror:1 row_mask:0xf bank_mask:0xf
	v_mov_b32_dpp v97, v84 row_shr:2 row_mask:0xf bank_mask:0xf
	v_fma_f32 v97, v68, v97, v60
	v_mov_b32_dpp v96, v84 row_shr:1 row_mask:0xf bank_mask:0xf
	v_fmac_f32_e32 v97, v72, v96
	v_fmac_f32_e32 v97, v84, v76
	v_mul_f32_e32 v96, 0xbfb8aa3b, v97
	v_exp_f32_e32 v96, v96
	v_mov_b32_dpp v98, v88 row_ror:2 row_mask:0xf bank_mask:0xf
	v_mov_b32_e32 v131, 0
	v_mov_b32_dpp v92, v88 row_ror:1 row_mask:0xf bank_mask:0xf
	v_add_f32_e32 v88, 1.0, v96
	v_rcp_f32_e32 v88, v88
	v_mov_b32_dpp v98, v80 row_shr:2 row_mask:0xf bank_mask:0xf
	v_mov_b32_dpp v92, v80 row_shr:1 row_mask:0xf bank_mask:0xf
	v_fma_f32 v96, v48, v98, v64
	v_fmac_f32_e32 v96, v52, v92
	v_fmac_f32_e32 v96, v80, v56
	v_mul_f32_e32 v88, v97, v88
	v_mul_f32_e32 v88, v96, v88
	v_mov_b32_dpp v96, v93 row_ror:2 row_mask:0xf bank_mask:0xf
	v_mov_b32_dpp v92, v93 row_ror:1 row_mask:0xf bank_mask:0xf
	v_mov_b32_dpp v96, v85 row_shr:2 row_mask:0xf bank_mask:0xf
	v_mov_b32_dpp v92, v85 row_shr:1 row_mask:0xf bank_mask:0xf
	v_fma_f32 v96, v69, v96, v61
	v_fmac_f32_e32 v96, v73, v92
	v_fmac_f32_e32 v96, v85, v77
	v_mul_f32_e32 v92, 0xbfb8aa3b, v96
	v_exp_f32_e32 v92, v92
	v_mov_b32_dpp v93, v89 row_ror:1 row_mask:0xf bank_mask:0xf
	v_mov_b32_dpp v97, v89 row_ror:2 row_mask:0xf bank_mask:0xf
	v_add_f32_e32 v89, 1.0, v92
	v_rcp_f32_e32 v89, v89
	v_mov_b32_dpp v97, v81 row_shr:2 row_mask:0xf bank_mask:0xf
	v_mov_b32_dpp v93, v81 row_shr:1 row_mask:0xf bank_mask:0xf
	v_fma_f32 v92, v49, v97, v65
	v_fmac_f32_e32 v92, v53, v93
	v_fmac_f32_e32 v92, v81, v57
	v_mul_f32_e32 v89, v96, v89
	v_mul_f32_e32 v89, v92, v89
	v_mov_b32_dpp v93, v94 row_ror:2 row_mask:0xf bank_mask:0xf
	v_mov_b32_dpp v92, v94 row_ror:1 row_mask:0xf bank_mask:0xf
	v_mov_b32_dpp v93, v86 row_shr:2 row_mask:0xf bank_mask:0xf
	v_fma_f32 v93, v70, v93, v62
	v_mov_b32_dpp v92, v86 row_shr:1 row_mask:0xf bank_mask:0xf
	v_fmac_f32_e32 v93, v74, v92
	v_fmac_f32_e32 v93, v86, v78
	v_mul_f32_e32 v92, 0xbfb8aa3b, v93
	v_exp_f32_e32 v92, v92
	v_mov_b32_dpp v96, v90 row_ror:2 row_mask:0xf bank_mask:0xf
	v_cvt_pk_bf16_f32 v146, v88, v89
	v_mov_b32_dpp v94, v90 row_ror:1 row_mask:0xf bank_mask:0xf
	v_add_f32_e32 v90, 1.0, v92
	v_rcp_f32_e32 v90, v90
	v_mov_b32_dpp v96, v82 row_shr:2 row_mask:0xf bank_mask:0xf
	v_mov_b32_dpp v94, v82 row_shr:1 row_mask:0xf bank_mask:0xf
	v_fma_f32 v92, v50, v96, v66
	v_fmac_f32_e32 v92, v54, v94
	v_fmac_f32_e32 v92, v82, v58
	v_mul_f32_e32 v90, v93, v90
	v_mul_f32_e32 v90, v92, v90
	v_mov_b32_dpp v93, v95 row_ror:2 row_mask:0xf bank_mask:0xf
	v_mov_b32_dpp v92, v95 row_ror:1 row_mask:0xf bank_mask:0xf
	v_mov_b32_dpp v93, v87 row_shr:2 row_mask:0xf bank_mask:0xf
	v_fma_f32 v93, v71, v93, v63
	v_mov_b32_dpp v92, v87 row_shr:1 row_mask:0xf bank_mask:0xf
	v_fmac_f32_e32 v93, v75, v92
	v_fmac_f32_e32 v93, v87, v79
	v_mul_f32_e32 v92, 0xbfb8aa3b, v93
	v_exp_f32_e32 v92, v92
	v_mov_b32_dpp v94, v91 row_ror:1 row_mask:0xf bank_mask:0xf
	v_mov_b32_dpp v95, v91 row_ror:2 row_mask:0xf bank_mask:0xf
	v_add_f32_e32 v91, 1.0, v92
	v_rcp_f32_e32 v91, v91
	v_mov_b32_dpp v95, v83 row_shr:2 row_mask:0xf bank_mask:0xf
	v_mov_b32_dpp v94, v83 row_shr:1 row_mask:0xf bank_mask:0xf
	v_fma_f32 v92, v51, v95, v67
	v_fmac_f32_e32 v92, v55, v94
	v_fmac_f32_e32 v92, v83, v59
	v_mul_f32_e32 v91, v93, v91
	v_mul_f32_e32 v91, v92, v91
	v_cvt_pk_bf16_f32 v147, v90, v91
	v_mov_b32_e32 v144, v242
	v_mov_b32_e32 v145, v243
	global_store_dwordx4 v[184:185], v[144:147], off
	v_mov_b32_dpp v89, v84 row_ror:2 row_mask:0xf bank_mask:0xf
	v_mov_b32_dpp v88, v84 row_ror:1 row_mask:0xf bank_mask:0xf
	v_mov_b32_dpp v89, v44 row_shr:2 row_mask:0xf bank_mask:0xf
	v_fma_f32 v89, v68, v89, v60
	v_mov_b32_dpp v88, v44 row_shr:1 row_mask:0xf bank_mask:0xf
	v_fmac_f32_e32 v89, v72, v88
	v_fmac_f32_e32 v89, v44, v76
	v_mul_f32_e32 v88, 0xbfb8aa3b, v89
	v_exp_f32_e32 v88, v88
	v_mov_b32_dpp v90, v80 row_ror:2 row_mask:0xf bank_mask:0xf
	s_nop 0
	v_mov_b32_dpp v84, v80 row_ror:1 row_mask:0xf bank_mask:0xf
	v_add_f32_e32 v80, 1.0, v88
	v_rcp_f32_e32 v80, v80
	v_mov_b32_dpp v90, v36 row_shr:2 row_mask:0xf bank_mask:0xf
	v_mov_b32_dpp v84, v36 row_shr:1 row_mask:0xf bank_mask:0xf
	v_fma_f32 v88, v48, v90, v64
	v_fmac_f32_e32 v88, v52, v84
	v_fmac_f32_e32 v88, v36, v56
	v_mul_f32_e32 v80, v89, v80
	v_mul_f32_e32 v80, v88, v80
	v_mov_b32_dpp v88, v85 row_ror:2 row_mask:0xf bank_mask:0xf
	v_mov_b32_dpp v84, v85 row_ror:1 row_mask:0xf bank_mask:0xf
	v_mov_b32_dpp v88, v45 row_shr:2 row_mask:0xf bank_mask:0xf
	v_mov_b32_dpp v84, v45 row_shr:1 row_mask:0xf bank_mask:0xf
	v_fma_f32 v88, v69, v88, v61
	v_fmac_f32_e32 v88, v73, v84
	v_fmac_f32_e32 v88, v45, v77
	v_mul_f32_e32 v84, 0xbfb8aa3b, v88
	v_exp_f32_e32 v84, v84
	v_mov_b32_dpp v85, v81 row_ror:1 row_mask:0xf bank_mask:0xf
	v_mov_b32_dpp v89, v81 row_ror:2 row_mask:0xf bank_mask:0xf
	v_add_f32_e32 v81, 1.0, v84
	v_rcp_f32_e32 v81, v81
	v_mov_b32_dpp v89, v37 row_shr:2 row_mask:0xf bank_mask:0xf
	v_mov_b32_dpp v85, v37 row_shr:1 row_mask:0xf bank_mask:0xf
	v_fma_f32 v84, v49, v89, v65
	v_fmac_f32_e32 v84, v53, v85
	v_fmac_f32_e32 v84, v37, v57
	v_mul_f32_e32 v81, v88, v81
	v_mul_f32_e32 v81, v84, v81
	v_mov_b32_dpp v85, v86 row_ror:2 row_mask:0xf bank_mask:0xf
	v_mov_b32_dpp v84, v86 row_ror:1 row_mask:0xf bank_mask:0xf
	v_mov_b32_dpp v85, v46 row_shr:2 row_mask:0xf bank_mask:0xf
	v_fma_f32 v85, v70, v85, v62
	v_mov_b32_dpp v84, v46 row_shr:1 row_mask:0xf bank_mask:0xf
	v_fmac_f32_e32 v85, v74, v84
	v_fmac_f32_e32 v85, v46, v78
	v_mul_f32_e32 v84, 0xbfb8aa3b, v85
	v_exp_f32_e32 v84, v84
	v_mov_b32_dpp v88, v82 row_ror:2 row_mask:0xf bank_mask:0xf
	v_cvt_pk_bf16_f32 v146, v80, v81
	v_mov_b32_dpp v86, v82 row_ror:1 row_mask:0xf bank_mask:0xf
	v_add_f32_e32 v82, 1.0, v84
	v_rcp_f32_e32 v82, v82
	v_mov_b32_dpp v88, v38 row_shr:2 row_mask:0xf bank_mask:0xf
	v_mov_b32_dpp v86, v38 row_shr:1 row_mask:0xf bank_mask:0xf
	v_fma_f32 v84, v50, v88, v66
	v_fmac_f32_e32 v84, v54, v86
	v_fmac_f32_e32 v84, v38, v58
	v_mul_f32_e32 v82, v85, v82
	v_mul_f32_e32 v82, v84, v82
	v_mov_b32_dpp v85, v87 row_ror:2 row_mask:0xf bank_mask:0xf
	v_mov_b32_dpp v84, v87 row_ror:1 row_mask:0xf bank_mask:0xf
	v_mov_b32_dpp v85, v47 row_shr:2 row_mask:0xf bank_mask:0xf
	v_fma_f32 v85, v71, v85, v63
	v_mov_b32_dpp v84, v47 row_shr:1 row_mask:0xf bank_mask:0xf
	v_fmac_f32_e32 v85, v75, v84
	v_fmac_f32_e32 v85, v47, v79
	v_mul_f32_e32 v84, 0xbfb8aa3b, v85
	v_exp_f32_e32 v84, v84
	v_mov_b32_dpp v86, v83 row_ror:1 row_mask:0xf bank_mask:0xf
	v_mov_b32_dpp v87, v83 row_ror:2 row_mask:0xf bank_mask:0xf
	v_add_f32_e32 v83, 1.0, v84
	v_rcp_f32_e32 v83, v83
	v_mov_b32_dpp v87, v39 row_shr:2 row_mask:0xf bank_mask:0xf
	v_mov_b32_dpp v86, v39 row_shr:1 row_mask:0xf bank_mask:0xf
	v_fma_f32 v84, v51, v87, v67
	v_fmac_f32_e32 v84, v55, v86
	v_fmac_f32_e32 v84, v39, v59
	v_mul_f32_e32 v83, v85, v83
	v_mul_f32_e32 v83, v84, v83
	v_cvt_pk_bf16_f32 v147, v82, v83
	v_mov_b32_e32 v144, v200
	v_mov_b32_e32 v145, v201
	global_store_dwordx4 v[176:177], v[144:147], off
	v_mov_b32_dpp v81, v44 row_ror:2 row_mask:0xf bank_mask:0xf
	s_nop 0
	v_mov_b32_dpp v80, v44 row_ror:1 row_mask:0xf bank_mask:0xf
	v_mov_b32_dpp v81, v40 row_shr:2 row_mask:0xf bank_mask:0xf
	v_fma_f32 v81, v68, v81, v60
	v_mov_b32_dpp v80, v40 row_shr:1 row_mask:0xf bank_mask:0xf
	v_fmac_f32_e32 v81, v72, v80
	v_fmac_f32_e32 v81, v40, v76
	v_mul_f32_e32 v40, 0xbfb8aa3b, v81
	v_exp_f32_e32 v40, v40
	s_nop 0
	v_mov_b32_dpp v44, v36 row_ror:1 row_mask:0xf bank_mask:0xf
	v_mov_b32_dpp v80, v36 row_ror:2 row_mask:0xf bank_mask:0xf
	v_add_f32_e32 v36, 1.0, v40
	v_rcp_f32_e32 v36, v36
	v_mov_b32_dpp v80, v32 row_shr:2 row_mask:0xf bank_mask:0xf
	v_mov_b32_dpp v44, v32 row_shr:1 row_mask:0xf bank_mask:0xf
	v_fma_f32 v40, v48, v80, v64
	v_fmac_f32_e32 v40, v52, v44
	v_fmac_f32_e32 v40, v32, v56
	v_mul_f32_e32 v32, v81, v36
	v_mul_f32_e32 v32, v40, v32
	v_mov_b32_dpp v40, v45 row_ror:2 row_mask:0xf bank_mask:0xf
	v_mov_b32_dpp v36, v45 row_ror:1 row_mask:0xf bank_mask:0xf
	v_mov_b32_dpp v44, v37 row_ror:1 row_mask:0xf bank_mask:0xf
	v_mov_b32_dpp v40, v41 row_shr:2 row_mask:0xf bank_mask:0xf
	v_mov_b32_dpp v36, v41 row_shr:1 row_mask:0xf bank_mask:0xf
	v_fma_f32 v40, v69, v40, v61
	v_fmac_f32_e32 v40, v73, v36
	v_fmac_f32_e32 v40, v41, v77
	v_mul_f32_e32 v36, 0xbfb8aa3b, v40
	v_exp_f32_e32 v36, v36
	v_mov_b32_dpp v44, v33 row_shr:1 row_mask:0xf bank_mask:0xf
	v_add_f32_e32 v36, 1.0, v36
	v_mov_b32_dpp v41, v37 row_ror:2 row_mask:0xf bank_mask:0xf
	v_rcp_f32_e32 v36, v36
	s_nop 0
	v_mov_b32_dpp v41, v33 row_shr:2 row_mask:0xf bank_mask:0xf
	v_fma_f32 v37, v49, v41, v65
	v_fmac_f32_e32 v37, v53, v44
	v_fmac_f32_e32 v37, v33, v57
	v_mul_f32_e32 v33, v40, v36
	v_mul_f32_e32 v33, v37, v33
	v_mov_b32_dpp v37, v46 row_ror:2 row_mask:0xf bank_mask:0xf
	v_mov_b32_dpp v36, v46 row_ror:1 row_mask:0xf bank_mask:0xf
	v_mov_b32_dpp v37, v42 row_shr:2 row_mask:0xf bank_mask:0xf
	v_mov_b32_dpp v36, v42 row_shr:1 row_mask:0xf bank_mask:0xf
	v_fma_f32 v37, v70, v37, v62
	v_fmac_f32_e32 v37, v74, v36
	v_fmac_f32_e32 v37, v42, v78
	v_mul_f32_e32 v36, 0xbfb8aa3b, v37
	v_exp_f32_e32 v36, v36
	v_mov_b32_dpp v41, v38 row_ror:2 row_mask:0xf bank_mask:0xf
	v_mov_b32_dpp v40, v38 row_ror:1 row_mask:0xf bank_mask:0xf
	v_cvt_pk_bf16_f32 v146, v32, v33
	v_add_f32_e32 v36, 1.0, v36
	v_rcp_f32_e32 v36, v36
	v_mov_b32_dpp v41, v34 row_shr:2 row_mask:0xf bank_mask:0xf
	v_mov_b32_dpp v40, v34 row_shr:1 row_mask:0xf bank_mask:0xf
	v_fma_f32 v38, v50, v41, v66
	v_fmac_f32_e32 v38, v54, v40
	v_fmac_f32_e32 v38, v34, v58
	v_mul_f32_e32 v34, v37, v36
	v_mov_b32_dpp v37, v47 row_ror:2 row_mask:0xf bank_mask:0xf
	v_mov_b32_dpp v36, v47 row_ror:1 row_mask:0xf bank_mask:0xf
	v_mul_f32_e32 v34, v38, v34
	v_mov_b32_dpp v37, v43 row_shr:2 row_mask:0xf bank_mask:0xf
	v_mov_b32_dpp v36, v43 row_shr:1 row_mask:0xf bank_mask:0xf
	v_fma_f32 v37, v71, v37, v63
	v_fmac_f32_e32 v37, v75, v36
	v_fmac_f32_e32 v37, v43, v79
	v_mul_f32_e32 v36, 0xbfb8aa3b, v37
	v_exp_f32_e32 v36, v36
	v_mov_b32_dpp v40, v39 row_ror:2 row_mask:0xf bank_mask:0xf
	v_add_f32_e32 v36, 1.0, v36
	v_rcp_f32_e32 v36, v36
	v_mov_b32_dpp v38, v39 row_ror:1 row_mask:0xf bank_mask:0xf
	v_mov_b32_dpp v40, v35 row_shr:2 row_mask:0xf bank_mask:0xf
	v_fma_f32 v39, v51, v40, v67
	v_mov_b32_dpp v38, v35 row_shr:1 row_mask:0xf bank_mask:0xf
	v_fmac_f32_e32 v39, v55, v38
	v_fmac_f32_e32 v39, v35, v59
	v_mul_f32_e32 v35, v37, v36
	v_mul_f32_e32 v35, v39, v35
	v_cvt_pk_bf16_f32 v147, v34, v35
	v_mov_b32_e32 v144, v226
	v_mov_b32_e32 v145, v227
	global_store_dwordx4 v[134:135], v[144:147], off
	v_mov_b32_e32 v32, 0
	v_mov_b32_e32 v33, 0
	v_mov_b32_e32 v34, 0
	v_mov_b32_e32 v35, 0
	s_and_saveexec_b64 s[54:55], s[4:5]
	s_cbranch_execz .LBB0_721
	ds_read_b128 v[128:131], v237
	ds_read_b128 v[32:35], v236
.LBB0_721:
	s_or_b64 exec, exec, s[54:55]
	s_waitcnt lgkmcnt(1)
	v_mov_b32_dpp v37, v128 row_ror:2 row_mask:0xf bank_mask:0xf
	v_mov_b32_dpp v36, v128 row_ror:1 row_mask:0xf bank_mask:0xf
	v_mov_b32_dpp v37, v28 row_shr:2 row_mask:0xf bank_mask:0xf
	v_mov_b32_dpp v36, v28 row_shr:1 row_mask:0xf bank_mask:0xf
	v_fma_f32 v37, v68, v37, v60
	v_fmac_f32_e32 v37, v72, v36
	v_fmac_f32_e32 v37, v28, v76
	v_mul_f32_e32 v36, 0xbfb8aa3b, v37
	v_exp_f32_e32 v36, v36
	s_waitcnt lgkmcnt(0)
	v_mov_b32_dpp v38, v32 row_ror:1 row_mask:0xf bank_mask:0xf
	v_mov_b32_dpp v39, v32 row_ror:2 row_mask:0xf bank_mask:0xf
	s_andn2_b64 vcc, exec, s[8:9]
	v_add_f32_e32 v32, 1.0, v36
	v_rcp_f32_e32 v32, v32
	v_mov_b32_dpp v39, v24 row_shr:2 row_mask:0xf bank_mask:0xf
	v_mov_b32_dpp v38, v24 row_shr:1 row_mask:0xf bank_mask:0xf
	v_fma_f32 v36, v48, v39, v64
	v_fmac_f32_e32 v36, v52, v38
	v_fmac_f32_e32 v36, v24, v56
	v_mul_f32_e32 v32, v37, v32
	v_mul_f32_e32 v32, v36, v32
	v_mov_b32_dpp v37, v129 row_ror:2 row_mask:0xf bank_mask:0xf
	v_mov_b32_dpp v36, v129 row_ror:1 row_mask:0xf bank_mask:0xf
	v_mov_b32_dpp v37, v29 row_shr:2 row_mask:0xf bank_mask:0xf
	v_fma_f32 v37, v69, v37, v61
	v_mov_b32_dpp v36, v29 row_shr:1 row_mask:0xf bank_mask:0xf
	v_fmac_f32_e32 v37, v73, v36
	v_fmac_f32_e32 v37, v29, v77
	v_mul_f32_e32 v36, 0xbfb8aa3b, v37
	v_exp_f32_e32 v36, v36
	v_mov_b32_dpp v38, v33 row_ror:1 row_mask:0xf bank_mask:0xf
	s_mov_b64 s[8:9], -1
	v_mov_b32_dpp v39, v33 row_ror:2 row_mask:0xf bank_mask:0xf
	v_add_f32_e32 v33, 1.0, v36
	v_rcp_f32_e32 v33, v33
	v_mov_b32_dpp v39, v25 row_shr:2 row_mask:0xf bank_mask:0xf
	v_mov_b32_dpp v38, v25 row_shr:1 row_mask:0xf bank_mask:0xf
	v_fma_f32 v36, v49, v39, v65
	v_fmac_f32_e32 v36, v53, v38
	v_fmac_f32_e32 v36, v25, v57
	v_mul_f32_e32 v33, v37, v33
	v_mul_f32_e32 v33, v36, v33
	v_mov_b32_dpp v37, v130 row_ror:2 row_mask:0xf bank_mask:0xf
	v_mov_b32_dpp v36, v130 row_ror:1 row_mask:0xf bank_mask:0xf
	v_mov_b32_dpp v37, v30 row_shr:2 row_mask:0xf bank_mask:0xf
	v_fma_f32 v37, v70, v37, v62
	v_mov_b32_dpp v36, v30 row_shr:1 row_mask:0xf bank_mask:0xf
	v_fmac_f32_e32 v37, v74, v36
	v_fmac_f32_e32 v37, v30, v78
	v_mul_f32_e32 v36, 0xbfb8aa3b, v37
	v_exp_f32_e32 v36, v36
	v_mov_b32_dpp v38, v34 row_ror:1 row_mask:0xf bank_mask:0xf
	v_cvt_pk_bf16_f32 v146, v32, v33
	v_mov_b32_dpp v39, v34 row_ror:2 row_mask:0xf bank_mask:0xf
	v_add_f32_e32 v34, 1.0, v36
	v_rcp_f32_e32 v34, v34
	v_mov_b32_dpp v39, v26 row_shr:2 row_mask:0xf bank_mask:0xf
	v_mov_b32_dpp v38, v26 row_shr:1 row_mask:0xf bank_mask:0xf
	v_fma_f32 v36, v50, v39, v66
	v_fmac_f32_e32 v36, v54, v38
	v_fmac_f32_e32 v36, v26, v58
	v_mul_f32_e32 v34, v37, v34
	v_mul_f32_e32 v34, v36, v34
	v_mov_b32_dpp v37, v131 row_ror:2 row_mask:0xf bank_mask:0xf
	v_mov_b32_dpp v36, v131 row_ror:1 row_mask:0xf bank_mask:0xf
	v_mov_b32_dpp v37, v31 row_shr:2 row_mask:0xf bank_mask:0xf
	v_fma_f32 v37, v71, v37, v63
	v_mov_b32_dpp v36, v31 row_shr:1 row_mask:0xf bank_mask:0xf
	v_fmac_f32_e32 v37, v75, v36
	v_fmac_f32_e32 v37, v31, v79
	v_mul_f32_e32 v36, 0xbfb8aa3b, v37
	v_exp_f32_e32 v36, v36
	v_mov_b32_dpp v38, v35 row_ror:1 row_mask:0xf bank_mask:0xf
	v_mov_b32_dpp v39, v35 row_ror:2 row_mask:0xf bank_mask:0xf
	v_add_f32_e32 v35, 1.0, v36
	v_rcp_f32_e32 v35, v35
	v_mov_b32_dpp v39, v27 row_shr:2 row_mask:0xf bank_mask:0xf
	v_mov_b32_dpp v38, v27 row_shr:1 row_mask:0xf bank_mask:0xf
	v_fma_f32 v36, v51, v39, v67
	v_fmac_f32_e32 v36, v55, v38
	v_fmac_f32_e32 v36, v27, v59
	v_mul_f32_e32 v35, v37, v35
	v_mul_f32_e32 v35, v36, v35
	v_cvt_pk_bf16_f32 v147, v34, v35
	v_mov_b32_e32 v144, v186
	v_mov_b32_e32 v145, v187
	global_store_dwordx4 v[132:133], v[144:147], off
	v_mov_b32_dpp v33, v28 row_ror:2 row_mask:0xf bank_mask:0xf
	v_mov_b32_dpp v32, v28 row_ror:1 row_mask:0xf bank_mask:0xf
	v_mov_b32_dpp v33, v20 row_shr:2 row_mask:0xf bank_mask:0xf
	v_fma_f32 v33, v68, v33, v60
	v_mov_b32_dpp v32, v20 row_shr:1 row_mask:0xf bank_mask:0xf
	v_fmac_f32_e32 v33, v72, v32
	v_fmac_f32_e32 v33, v20, v76
	v_mul_f32_e32 v32, 0xbfb8aa3b, v33
	v_exp_f32_e32 v32, v32
	v_mov_b32_dpp v34, v24 row_ror:2 row_mask:0xf bank_mask:0xf
	s_nop 0
	v_mov_b32_dpp v28, v24 row_ror:1 row_mask:0xf bank_mask:0xf
	v_add_f32_e32 v24, 1.0, v32
	v_rcp_f32_e32 v24, v24
	v_mov_b32_dpp v34, v16 row_shr:2 row_mask:0xf bank_mask:0xf
	v_mov_b32_dpp v28, v16 row_shr:1 row_mask:0xf bank_mask:0xf
	v_fma_f32 v32, v48, v34, v64
	v_fmac_f32_e32 v32, v52, v28
	v_fmac_f32_e32 v32, v16, v56
	v_mul_f32_e32 v24, v33, v24
	v_mul_f32_e32 v24, v32, v24
	v_mov_b32_dpp v32, v29 row_ror:2 row_mask:0xf bank_mask:0xf
	v_mov_b32_dpp v28, v29 row_ror:1 row_mask:0xf bank_mask:0xf
	v_mov_b32_dpp v32, v21 row_shr:2 row_mask:0xf bank_mask:0xf
	v_mov_b32_dpp v28, v21 row_shr:1 row_mask:0xf bank_mask:0xf
	v_fma_f32 v32, v69, v32, v61
	v_fmac_f32_e32 v32, v73, v28
	v_fmac_f32_e32 v32, v21, v77
	v_mul_f32_e32 v28, 0xbfb8aa3b, v32
	v_exp_f32_e32 v28, v28
	v_mov_b32_dpp v29, v25 row_ror:1 row_mask:0xf bank_mask:0xf
	v_mov_b32_dpp v33, v25 row_ror:2 row_mask:0xf bank_mask:0xf
	v_add_f32_e32 v25, 1.0, v28
	v_rcp_f32_e32 v25, v25
	v_mov_b32_dpp v33, v17 row_shr:2 row_mask:0xf bank_mask:0xf
	v_mov_b32_dpp v29, v17 row_shr:1 row_mask:0xf bank_mask:0xf
	v_fma_f32 v28, v49, v33, v65
	v_fmac_f32_e32 v28, v53, v29
	v_fmac_f32_e32 v28, v17, v57
	v_mul_f32_e32 v25, v32, v25
	v_mul_f32_e32 v25, v28, v25
	v_mov_b32_dpp v29, v30 row_ror:2 row_mask:0xf bank_mask:0xf
	v_mov_b32_dpp v28, v30 row_ror:1 row_mask:0xf bank_mask:0xf
	v_mov_b32_dpp v29, v22 row_shr:2 row_mask:0xf bank_mask:0xf
	v_fma_f32 v29, v70, v29, v62
	v_mov_b32_dpp v28, v22 row_shr:1 row_mask:0xf bank_mask:0xf
	v_fmac_f32_e32 v29, v74, v28
	v_fmac_f32_e32 v29, v22, v78
	v_mul_f32_e32 v28, 0xbfb8aa3b, v29
	v_exp_f32_e32 v28, v28
	v_mov_b32_dpp v32, v26 row_ror:2 row_mask:0xf bank_mask:0xf
	v_cvt_pk_bf16_f32 v146, v24, v25
	v_mov_b32_dpp v30, v26 row_ror:1 row_mask:0xf bank_mask:0xf
	v_add_f32_e32 v26, 1.0, v28
	v_rcp_f32_e32 v26, v26
	v_mov_b32_dpp v32, v18 row_shr:2 row_mask:0xf bank_mask:0xf
	v_mov_b32_dpp v30, v18 row_shr:1 row_mask:0xf bank_mask:0xf
	v_fma_f32 v28, v50, v32, v66
	v_fmac_f32_e32 v28, v54, v30
	v_fmac_f32_e32 v28, v18, v58
	v_mul_f32_e32 v26, v29, v26
	v_mul_f32_e32 v26, v28, v26
	v_mov_b32_dpp v29, v31 row_ror:2 row_mask:0xf bank_mask:0xf
	v_mov_b32_dpp v28, v31 row_ror:1 row_mask:0xf bank_mask:0xf
	v_mov_b32_dpp v29, v23 row_shr:2 row_mask:0xf bank_mask:0xf
	v_fma_f32 v29, v71, v29, v63
	v_mov_b32_dpp v28, v23 row_shr:1 row_mask:0xf bank_mask:0xf
	v_fmac_f32_e32 v29, v75, v28
	v_fmac_f32_e32 v29, v23, v79
	v_mul_f32_e32 v28, 0xbfb8aa3b, v29
	v_exp_f32_e32 v28, v28
	v_mov_b32_dpp v30, v27 row_ror:1 row_mask:0xf bank_mask:0xf
	v_mov_b32_dpp v31, v27 row_ror:2 row_mask:0xf bank_mask:0xf
	v_add_f32_e32 v27, 1.0, v28
	v_rcp_f32_e32 v27, v27
	v_mov_b32_dpp v31, v19 row_shr:2 row_mask:0xf bank_mask:0xf
	v_mov_b32_dpp v30, v19 row_shr:1 row_mask:0xf bank_mask:0xf
	v_fma_f32 v28, v51, v31, v67
	v_fmac_f32_e32 v28, v55, v30
	v_fmac_f32_e32 v28, v19, v59
	v_mul_f32_e32 v27, v29, v27
	v_mul_f32_e32 v27, v28, v27
	v_cvt_pk_bf16_f32 v147, v26, v27
	v_mov_b32_e32 v144, v188
	v_mov_b32_e32 v145, v189
	global_store_dwordx4 v[120:121], v[144:147], off
	v_mov_b32_dpp v25, v20 row_ror:2 row_mask:0xf bank_mask:0xf
	v_mov_b32_dpp v24, v20 row_ror:1 row_mask:0xf bank_mask:0xf
	v_mov_b32_dpp v25, v12 row_shr:2 row_mask:0xf bank_mask:0xf
	v_fma_f32 v25, v68, v25, v60
	v_mov_b32_dpp v24, v12 row_shr:1 row_mask:0xf bank_mask:0xf
	v_fmac_f32_e32 v25, v72, v24
	v_fmac_f32_e32 v25, v12, v76
	v_mul_f32_e32 v24, 0xbfb8aa3b, v25
	v_exp_f32_e32 v24, v24
	v_mov_b32_dpp v26, v16 row_ror:2 row_mask:0xf bank_mask:0xf
	s_nop 0
	v_mov_b32_dpp v20, v16 row_ror:1 row_mask:0xf bank_mask:0xf
	v_add_f32_e32 v16, 1.0, v24
	v_rcp_f32_e32 v16, v16
	v_mov_b32_dpp v26, v4 row_shr:2 row_mask:0xf bank_mask:0xf
	v_mov_b32_dpp v20, v4 row_shr:1 row_mask:0xf bank_mask:0xf
	v_fma_f32 v24, v48, v26, v64
	v_fmac_f32_e32 v24, v52, v20
	v_fmac_f32_e32 v24, v4, v56
	v_mul_f32_e32 v16, v25, v16
	v_mul_f32_e32 v16, v24, v16
	v_mov_b32_dpp v24, v21 row_ror:2 row_mask:0xf bank_mask:0xf
	v_mov_b32_dpp v20, v21 row_ror:1 row_mask:0xf bank_mask:0xf
	v_mov_b32_dpp v24, v13 row_shr:2 row_mask:0xf bank_mask:0xf
	v_mov_b32_dpp v20, v13 row_shr:1 row_mask:0xf bank_mask:0xf
	v_fma_f32 v24, v69, v24, v61
	v_fmac_f32_e32 v24, v73, v20
	v_fmac_f32_e32 v24, v13, v77
	v_mul_f32_e32 v20, 0xbfb8aa3b, v24
	v_exp_f32_e32 v20, v20
	v_mov_b32_dpp v21, v17 row_ror:1 row_mask:0xf bank_mask:0xf
	v_mov_b32_dpp v25, v17 row_ror:2 row_mask:0xf bank_mask:0xf
	v_add_f32_e32 v17, 1.0, v20
	v_rcp_f32_e32 v17, v17
	v_mov_b32_dpp v25, v5 row_shr:2 row_mask:0xf bank_mask:0xf
	v_mov_b32_dpp v21, v5 row_shr:1 row_mask:0xf bank_mask:0xf
	v_fma_f32 v20, v49, v25, v65
	v_fmac_f32_e32 v20, v53, v21
	v_fmac_f32_e32 v20, v5, v57
	v_mul_f32_e32 v17, v24, v17
	v_mul_f32_e32 v17, v20, v17
	v_mov_b32_dpp v21, v22 row_ror:2 row_mask:0xf bank_mask:0xf
	v_mov_b32_dpp v20, v22 row_ror:1 row_mask:0xf bank_mask:0xf
	v_mov_b32_dpp v21, v14 row_shr:2 row_mask:0xf bank_mask:0xf
	v_fma_f32 v21, v70, v21, v62
	v_mov_b32_dpp v20, v14 row_shr:1 row_mask:0xf bank_mask:0xf
	v_fmac_f32_e32 v21, v74, v20
	v_fmac_f32_e32 v21, v14, v78
	v_mul_f32_e32 v20, 0xbfb8aa3b, v21
	v_exp_f32_e32 v20, v20
	v_mov_b32_dpp v24, v18 row_ror:2 row_mask:0xf bank_mask:0xf
	v_cvt_pk_bf16_f32 v146, v16, v17
	v_mov_b32_dpp v22, v18 row_ror:1 row_mask:0xf bank_mask:0xf
	v_add_f32_e32 v18, 1.0, v20
	v_rcp_f32_e32 v18, v18
	v_mov_b32_dpp v24, v6 row_shr:2 row_mask:0xf bank_mask:0xf
	v_mov_b32_dpp v22, v6 row_shr:1 row_mask:0xf bank_mask:0xf
	v_fma_f32 v20, v50, v24, v66
	v_fmac_f32_e32 v20, v54, v22
	v_fmac_f32_e32 v20, v6, v58
	v_mul_f32_e32 v18, v21, v18
	v_mul_f32_e32 v18, v20, v18
	v_mov_b32_dpp v21, v23 row_ror:2 row_mask:0xf bank_mask:0xf
	v_mov_b32_dpp v20, v23 row_ror:1 row_mask:0xf bank_mask:0xf
	v_mov_b32_dpp v21, v15 row_shr:2 row_mask:0xf bank_mask:0xf
	v_fma_f32 v21, v71, v21, v63
	v_mov_b32_dpp v20, v15 row_shr:1 row_mask:0xf bank_mask:0xf
	v_fmac_f32_e32 v21, v75, v20
	v_fmac_f32_e32 v21, v15, v79
	v_mul_f32_e32 v20, 0xbfb8aa3b, v21
	v_exp_f32_e32 v20, v20
	v_mov_b32_dpp v22, v19 row_ror:1 row_mask:0xf bank_mask:0xf
	v_mov_b32_dpp v23, v19 row_ror:2 row_mask:0xf bank_mask:0xf
	v_add_f32_e32 v19, 1.0, v20
	v_rcp_f32_e32 v19, v19
	v_mov_b32_dpp v23, v7 row_shr:2 row_mask:0xf bank_mask:0xf
	v_mov_b32_dpp v22, v7 row_shr:1 row_mask:0xf bank_mask:0xf
	v_fma_f32 v20, v51, v23, v67
	v_fmac_f32_e32 v20, v55, v22
	v_fmac_f32_e32 v20, v7, v59
	v_mul_f32_e32 v19, v21, v19
	v_mul_f32_e32 v19, v20, v19
	v_cvt_pk_bf16_f32 v147, v18, v19
	v_mov_b32_e32 v144, v190
	v_mov_b32_e32 v145, v191
	global_store_dwordx4 v[112:113], v[144:147], off
	v_mov_b32_dpp v17, v12 row_ror:2 row_mask:0xf bank_mask:0xf
	s_nop 0
	v_mov_b32_dpp v16, v12 row_ror:1 row_mask:0xf bank_mask:0xf
	v_mov_b32_dpp v17, v8 row_shr:2 row_mask:0xf bank_mask:0xf
	v_fma_f32 v17, v68, v17, v60
	v_mov_b32_dpp v16, v8 row_shr:1 row_mask:0xf bank_mask:0xf
	v_fmac_f32_e32 v17, v72, v16
	v_fmac_f32_e32 v17, v8, v76
	v_mul_f32_e32 v8, 0xbfb8aa3b, v17
	v_exp_f32_e32 v8, v8
	s_nop 0
	v_mov_b32_dpp v12, v4 row_ror:1 row_mask:0xf bank_mask:0xf
	v_mov_b32_dpp v16, v4 row_ror:2 row_mask:0xf bank_mask:0xf
	v_add_f32_e32 v4, 1.0, v8
	v_rcp_f32_e32 v4, v4
	v_mov_b32_dpp v16, v0 row_shr:2 row_mask:0xf bank_mask:0xf
	v_mov_b32_dpp v12, v0 row_shr:1 row_mask:0xf bank_mask:0xf
	v_fma_f32 v8, v48, v16, v64
	v_fmac_f32_e32 v8, v52, v12
	v_fmac_f32_e32 v8, v0, v56
	v_mul_f32_e32 v0, v17, v4
	v_mul_f32_e32 v0, v8, v0
	v_mov_b32_dpp v8, v13 row_ror:2 row_mask:0xf bank_mask:0xf
	v_mov_b32_dpp v4, v13 row_ror:1 row_mask:0xf bank_mask:0xf
	v_mov_b32_dpp v12, v5 row_ror:1 row_mask:0xf bank_mask:0xf
	v_mov_b32_dpp v8, v9 row_shr:2 row_mask:0xf bank_mask:0xf
	v_mov_b32_dpp v4, v9 row_shr:1 row_mask:0xf bank_mask:0xf
	v_fma_f32 v8, v69, v8, v61
	v_fmac_f32_e32 v8, v73, v4
	v_fmac_f32_e32 v8, v9, v77
	v_mul_f32_e32 v4, 0xbfb8aa3b, v8
	v_exp_f32_e32 v4, v4
	v_mov_b32_dpp v12, v1 row_shr:1 row_mask:0xf bank_mask:0xf
	v_add_f32_e32 v4, 1.0, v4
	v_mov_b32_dpp v9, v5 row_ror:2 row_mask:0xf bank_mask:0xf
	v_rcp_f32_e32 v4, v4
	s_nop 0
	v_mov_b32_dpp v9, v1 row_shr:2 row_mask:0xf bank_mask:0xf
	v_fma_f32 v5, v49, v9, v65
	v_fmac_f32_e32 v5, v53, v12
	v_fmac_f32_e32 v5, v1, v57
	v_mul_f32_e32 v1, v8, v4
	v_mul_f32_e32 v1, v5, v1
	v_mov_b32_dpp v5, v14 row_ror:2 row_mask:0xf bank_mask:0xf
	v_mov_b32_dpp v4, v14 row_ror:1 row_mask:0xf bank_mask:0xf
	v_mov_b32_dpp v5, v10 row_shr:2 row_mask:0xf bank_mask:0xf
	v_mov_b32_dpp v4, v10 row_shr:1 row_mask:0xf bank_mask:0xf
	v_fma_f32 v5, v70, v5, v62
	v_fmac_f32_e32 v5, v74, v4
	v_fmac_f32_e32 v5, v10, v78
	v_mul_f32_e32 v4, 0xbfb8aa3b, v5
	v_exp_f32_e32 v4, v4
	v_mov_b32_dpp v9, v6 row_ror:2 row_mask:0xf bank_mask:0xf
	v_mov_b32_dpp v8, v6 row_ror:1 row_mask:0xf bank_mask:0xf
	v_cvt_pk_bf16_f32 v146, v0, v1
	v_add_f32_e32 v4, 1.0, v4
	v_rcp_f32_e32 v4, v4
	v_mov_b32_dpp v9, v2 row_shr:2 row_mask:0xf bank_mask:0xf
	v_mov_b32_dpp v8, v2 row_shr:1 row_mask:0xf bank_mask:0xf
	v_fma_f32 v6, v50, v9, v66
	v_fmac_f32_e32 v6, v54, v8
	v_fmac_f32_e32 v6, v2, v58
	v_mul_f32_e32 v2, v5, v4
	v_mul_f32_e32 v2, v6, v2
	v_mov_b32_dpp v5, v15 row_ror:2 row_mask:0xf bank_mask:0xf
	v_mov_b32_dpp v4, v15 row_ror:1 row_mask:0xf bank_mask:0xf
	v_mov_b32_dpp v5, v11 row_shr:2 row_mask:0xf bank_mask:0xf
	v_mov_b32_dpp v4, v11 row_shr:1 row_mask:0xf bank_mask:0xf
	v_fmac_f32_e32 v63, v71, v5
	v_fmac_f32_e32 v63, v75, v4
	v_fmac_f32_e32 v63, v11, v79
	v_mul_f32_e32 v4, 0xbfb8aa3b, v63
	v_exp_f32_e32 v4, v4
	v_mov_b32_dpp v6, v7 row_ror:1 row_mask:0xf bank_mask:0xf
	v_add_f32_e32 v4, 1.0, v4
	v_mov_b32_dpp v5, v7 row_ror:2 row_mask:0xf bank_mask:0xf
	v_rcp_f32_e32 v4, v4
	v_mov_b32_dpp v6, v3 row_shr:1 row_mask:0xf bank_mask:0xf
	v_mov_b32_dpp v5, v3 row_shr:2 row_mask:0xf bank_mask:0xf
	v_fmac_f32_e32 v67, v51, v5
	v_fmac_f32_e32 v67, v55, v6
	v_fmac_f32_e32 v67, v3, v59
	v_mul_f32_e32 v3, v63, v4
	v_mul_f32_e32 v3, v67, v3
	v_cvt_pk_bf16_f32 v147, v2, v3
	v_mov_b32_e32 v144, v192
	v_mov_b32_e32 v145, v193
	global_store_dwordx4 v[104:105], v[144:147], off
	s_cbranch_vccnz .LBB0_701
	s_and_b64 vcc, exec, s[10:11]
	s_cbranch_vccnz .LBB0_700
	s_barrier
	s_branch .LBB0_700
	s_nop 0
	s_nop 0
	s_nop 0
	s_nop 0
	s_nop 0
	s_nop 0
	s_nop 0
	s_nop 0
	s_nop 0
	s_nop 0
	s_nop 0
	s_nop 0
	s_nop 0
	s_nop 0
	s_nop 0
	s_nop 0
	s_nop 0
	s_nop 0
	s_nop 0
	s_nop 0
	s_nop 0
	s_nop 0
	s_nop 0
	s_nop 0
	s_nop 0
	s_nop 0
	s_nop 0
	s_nop 0
	s_nop 0
	s_nop 0
	s_nop 0
	s_nop 0
